# P2: peeled last K-trip issues 3 of the unit's stores early (block 0 is final after phase 5), one per phase; plus swa K-staging and hgrn_out S_prev copies de-serialised
# speedup vs baseline: 1.0324x; 1.0060x over previous
.LBB0_210:
	s_or_b64 exec, exec, s[6:7]
	s_mov_b64 s[6:7], s[62:63]
	s_waitcnt lgkmcnt(0)
	s_barrier
	s_load_dwordx2 s[60:61], s[62:63], 0xc0
	s_waitcnt lgkmcnt(0)
	global_load_dwordx2 v[0:1], v167, s[6:7] offset:192
	s_mov_b64 s[6:7], 0x5300000
	s_bitcmp1_b32 s83, 0
	s_cselect_b32 s96, 0x1880000, 0
	v_readlane_b32 s10, v253, 5
	s_mov_b64 s[8:9], s[62:63]
	v_mov_b32_e32 v20, v208
	v_readlane_b32 s11, v253, 6
	s_and_b64 vcc, exec, s[10:11]
	s_waitcnt vmcnt(0)
	v_lshl_add_u64 v[0:1], v[0:1], 0, s[6:7]
	s_mov_b64 s[6:7], s[62:63]
	global_load_dwordx2 v[2:3], v167, s[6:7] offset:192
	v_readfirstlane_b32 s5, v1
	v_readfirstlane_b32 s24, v0
	s_movk_i32 s6, 0x400
	v_readfirstlane_b32 s25, v20
	s_waitcnt vmcnt(0)
	v_lshl_add_u64 v[2:3], v[2:3], 0, s[96:97]
	s_nop 0
	v_readfirstlane_b32 s26, v3
	v_readfirstlane_b32 s27, v2
	s_cbranch_vccz .LBB0_228
	v_lshlrev_b32_e32 v2, 4, v20
	v_add_u32_e32 v3, 0x2000, v2
	v_ashrrev_i32_e32 v4, 31, v3
	v_lshrrev_b32_e32 v4, 22, v4
	v_add_u32_e32 v4, v3, v4
	v_ashrrev_i32_e32 v4, 10, v4
	v_mul_i32_i24_e32 v5, 0x400, v4
	v_sub_u32_e32 v3, v3, v5
	v_lshrrev_b32_e32 v5, 4, v3
	v_bitop3_b32 v3, v5, v3, 32 bitop3:0x6c
	v_ashrrev_i32_e32 v5, 31, v3
	v_lshrrev_b32_e32 v5, 26, v5
	v_add_u32_e32 v5, v3, v5
	v_lshlrev_b32_e32 v7, 3, v4
	v_ashrrev_i32_e32 v6, 6, v5
	v_and_b32_e32 v7, -16, v7
	v_add_u32_e32 v7, v6, v7
	v_and_b32_e32 v6, 3, v6
	s_mov_b32 s0, 0x7fffffe0
	v_lshrrev_b32_e32 v8, 2, v7
	v_lshlrev_b32_e32 v9, 1, v7
	v_lshlrev_b32_e32 v4, 5, v4
	v_and_or_b32 v6, v7, s0, v6
	v_and_b32_e32 v8, 4, v8
	v_and_b32_e32 v9, 24, v9
	v_and_b32_e32 v14, 32, v4
	v_and_b32_e32 v4, 0xc0, v5
	v_or3_b32 v6, v6, v8, v9
	v_sub_u32_e32 v3, v3, v4
	v_mov_b32_e32 v9, 1
	v_ashrrev_i16_sdwa v3, v9, sext(v3) dst_sel:DWORD dst_unused:UNUSED_PAD src0_sel:DWORD src1_sel:BYTE_0
	v_bfe_i32 v15, v3, 0, 16
	v_mul_lo_u32 v6, v6, s6
	v_add_u32_e32 v3, v14, v15
	v_mul_lo_u32 v16, v7, s6
	v_add_lshl_u32 v132, v6, v3, 1
	v_add_lshl_u32 v134, v3, v16, 1
	v_bfe_i32 v3, v20, 27, 1
	v_lshrrev_b32_e32 v3, 22, v3
	v_add_u32_e32 v3, v2, v3
	v_and_b32_e32 v3, 0xfffffc00, v3
	v_sub_u32_e32 v2, v2, v3
	v_ashrrev_i32_e32 v4, 31, v20
	v_lshrrev_b32_e32 v3, 4, v2
	v_lshrrev_b32_e32 v4, 26, v4
	v_bitop3_b32 v3, v3, v2, 32 bitop3:0x6c
	v_ashrrev_i32_e32 v2, 31, v2
	v_add_u32_e32 v4, v20, v4
	v_lshrrev_b32_e32 v2, 26, v2
	v_ashrrev_i32_e32 v4, 6, v4
	v_add_u32_e32 v2, v3, v2
	v_lshlrev_b32_e32 v5, 3, v4
	v_ashrrev_i32_e32 v2, 6, v2
	v_and_b32_e32 v5, -16, v5
	s_ashr_i32 s7, s6, 31
	v_add_u32_e32 v5, v2, v5
	v_and_b32_e32 v6, 3, v2
	s_lshl_b64 s[14:15], s[6:7], 9
	v_and_or_b32 v6, v5, s0, v6
	v_readlane_b32 s0, v253, 42
	s_mul_i32 s10, s14, s0
	v_readlane_b32 s0, v253, 41
	v_readlane_b32 s20, v253, 43
	s_mul_hi_u32 s11, s14, s0
	v_readlane_b32 s21, v253, 44
	v_mul_i32_i24_e32 v2, 64, v2
	s_add_i32 s16, s11, s10
	s_lshr_b64 s[10:11], s[6:7], 23
	s_mul_i32 s17, s14, s21
	s_mul_hi_u32 s18, s14, s20
	global_load_dwordx2 v[0:1], v167, s[8:9] offset:192
	s_ashr_i32 s8, s25, 6
	v_lshrrev_b32_e32 v7, 2, v5
	v_lshlrev_b32_e32 v8, 1, v5
	v_sub_u32_e32 v2, v3, v2
	s_mul_i32 s11, s10, s0
	s_add_i32 s17, s18, s17
	s_mul_i32 s10, s10, s20
	s_ashr_i32 s9, s25, 8
	s_lshl_b64 s[12:13], s[6:7], 8
	s_lshl_b32 s28, s8, 10
	v_and_b32_e32 v7, 4, v7
	v_and_b32_e32 v8, 24, v8
	v_lshlrev_b32_e32 v4, 5, v4
	v_ashrrev_i16_sdwa v2, v9, sext(v2) dst_sel:DWORD dst_unused:UNUSED_PAD src0_sel:DWORD src1_sel:BYTE_0
	s_add_i32 s16, s16, s11
	s_add_i32 s17, s17, s10
	s_mul_i32 s10, s14, s20
	v_or3_b32 v6, v6, v7, v8
	v_and_b32_e32 v17, 32, v4
	v_bfe_i32 v18, v2, 0, 16
	s_add_u32 s18, s27, s10
	v_mul_lo_u32 v6, v6, s6
	v_add_u32_e32 v2, v17, v18
	s_addc_u32 s19, s26, s17
	s_add_i32 s29, s28, 0
	v_add_lshl_u32 v166, v6, v2, 1
	s_add_i32 m0, s29, 0x10000
	s_mul_i32 s11, s14, s0
	global_load_lds_dwordx4 v166, s[18:19]
	s_add_i32 m0, s29, 0x12000
	v_mul_lo_u32 v19, v5, s6
	s_add_u32 s20, s24, s11
	v_add_lshl_u32 v136, v2, v19, 1
	global_load_lds_dwordx4 v132, s[18:19]
	s_addc_u32 s21, s5, s16
	s_mov_b32 m0, s29
	s_add_i32 s30, s29, 0x2000
	global_load_lds_dwordx4 v136, s[20:21]
	s_mov_b32 m0, s30
	s_add_u32 s10, s18, s12
	global_load_lds_dwordx4 v134, s[20:21]
	s_addc_u32 s11, s19, s13
	s_add_i32 m0, s29, 0x14000
	v_mov_b32_e32 v133, v167
	global_load_lds_dwordx4 v166, s[10:11]
	s_add_i32 m0, s29, 0x16000
	v_lshl_add_u64 v[10:11], s[10:11], 0, v[166:167]
	v_lshl_add_u64 v[12:13], s[10:11], 0, v[132:133]
	global_load_lds_dwordx4 v132, s[10:11]
	s_add_u32 s10, s20, s12
	s_addc_u32 s11, s21, s13
	s_add_i32 s31, s29, 0x4000
	s_mov_b32 m0, s31
	s_add_i32 s34, s29, 0x6000
	global_load_lds_dwordx4 v136, s[10:11]
	s_mov_b32 m0, s34
	v_mov_b32_e32 v137, v167
	global_load_lds_dwordx4 v134, s[10:11]
	v_mov_b32_e32 v135, v167
	v_lshl_add_u64 v[2:3], s[18:19], 0, v[166:167]
	v_lshl_add_u64 v[4:5], s[18:19], 0, v[132:133]
	v_lshl_add_u64 v[6:7], s[20:21], 0, v[136:137]
	v_lshl_add_u64 v[8:9], s[20:21], 0, v[134:135]
	s_cmp_lg_u32 s9, 1
	s_cbranch_scc1 .LBB0_213
	s_barrier
.LBB0_213:
	s_add_i32 m0, s29, 0x18000
	v_lshl_add_u64 v[2:3], v[2:3], 0, s[88:89]
	s_waitcnt vmcnt(4)
	s_barrier
	global_load_lds_dwordx4 v[2:3], off
	v_lshl_add_u64 v[2:3], v[4:5], 0, s[88:89]
	s_add_i32 m0, s29, 0x1a000
	s_add_i32 s36, s29, 0x8000
	global_load_lds_dwordx4 v[2:3], off
	v_lshl_add_u64 v[2:3], v[6:7], 0, s[88:89]
	s_mov_b32 m0, s36
	s_add_i32 s37, s29, 0xa000
	global_load_lds_dwordx4 v[2:3], off
	v_lshl_add_u64 v[2:3], v[8:9], 0, s[88:89]
	s_mov_b32 m0, s37
	s_lshr_b32 s7, s7, 26
	global_load_lds_dwordx4 v[2:3], off
	s_add_i32 m0, s29, 0x1c000
	v_lshl_add_u64 v[2:3], v[10:11], 0, s[88:89]
	global_load_lds_dwordx4 v[2:3], off
	v_lshl_add_u64 v[2:3], v[12:13], 0, s[88:89]
	s_add_i32 m0, s29, 0x1e000
	v_and_b32_e32 v21, 15, v20
	global_load_lds_dwordx4 v[2:3], off
	s_add_i32 s7, s6, s7
	v_and_b32_e32 v24, 48, v20
	v_lshlrev_b32_e32 v20, 2, v20
	s_ashr_i32 s35, s7, 6
	v_lshl_or_b32 v22, s9, 6, v21
	v_lshl_or_b32 v21, v21, 6, v24
	s_lshl_b32 s7, s9, 13
	v_and_b32_e32 v20, 32, v20
	v_bitop3_b32 v26, v21, s7, v20 bitop3:0xde
	s_lshl_b32 s7, s8, 5
	s_and_b32 s7, s7, 0x60
	s_mov_b64 s[10:11], 0x74c2800
	s_lshl_b32 s8, s7, 7
	v_ashrrev_i32_e32 v23, 31, v22
	s_waitcnt vmcnt(0)
	v_lshl_add_u64 v[0:1], v[0:1], 0, s[10:11]
	s_cmp_gt_i32 s6, 63
	v_lshlrev_b64 v[2:3], 9, v[22:23]
	v_or_b32_e32 v4, 16, v22
	s_cselect_b64 s[16:17], -1, 0
	v_ashrrev_i32_e32 v5, 31, v4
	v_lshl_add_u64 v[2:3], v[0:1], 0, v[2:3]
	s_lshl_b32 s96, s7, 1
	v_lshlrev_b64 v[4:5], 9, v[4:5]
	v_or_b32_e32 v6, 32, v22
	v_or_b32_e32 v8, 48, v22
	v_lshl_add_u64 v[2:3], v[2:3], 0, s[96:97]
	v_mov_b32_e32 v25, v167
	v_ashrrev_i32_e32 v7, 31, v6
	v_ashrrev_i32_e32 v9, 31, v8
	v_lshl_add_u64 v[138:139], v[2:3], 0, v[24:25]
	v_lshl_add_u64 v[2:3], v[0:1], 0, v[4:5]
	v_lshlrev_b64 v[6:7], 9, v[6:7]
	v_lshlrev_b64 v[8:9], 9, v[8:9]
	v_lshl_add_u64 v[2:3], v[2:3], 0, s[96:97]
	v_lshl_add_u64 v[140:141], v[2:3], 0, v[24:25]
	v_lshl_add_u64 v[2:3], v[0:1], 0, v[6:7]
	v_lshl_add_u64 v[0:1], v[0:1], 0, v[8:9]
	v_lshl_add_u64 v[0:1], v[0:1], 0, s[96:97]
	v_lshl_add_u64 v[144:145], v[0:1], 0, v[24:25]
	s_mov_b64 s[6:7], 0x10000
	v_add_u32_e32 v0, v16, v14
	v_lshl_add_u64 v[146:147], v[138:139], 0, s[6:7]
	s_mov_b64 s[6:7], 0x12000
	v_add_lshl_u32 v0, v0, v15, 1
	v_mov_b32_e32 v1, v167
	s_waitcnt vmcnt(6)
	v_lshl_add_u64 v[148:149], v[138:139], 0, s[6:7]
	s_mov_b64 s[6:7], 0x14000
	v_lshl_add_u64 v[154:155], s[12:13], 0, v[0:1]
	v_add_u32_e32 v0, v19, v17
	v_lshl_add_u64 v[2:3], v[2:3], 0, s[96:97]
	v_lshl_add_u64 v[150:151], v[138:139], 0, s[6:7]
	s_mov_b64 s[6:7], 0x16000
	v_add_lshl_u32 v0, v0, v18, 1
	v_bitop3_b32 v158, v21, s8, v20 bitop3:0xde
	s_add_i32 s38, s35, -2
	v_lshl_add_u64 v[142:143], v[2:3], 0, v[24:25]
	v_lshl_add_u64 v[152:153], v[138:139], 0, s[6:7]
	v_lshl_add_u64 v[156:157], s[12:13], 0, v[0:1]
	s_mov_b32 s39, 0
	v_add_u32_e32 v159, 0, v26
	v_readlane_b32 s42, v253, 40
	v_readlane_b32 s43, v253, 41
	s_barrier
	v_lshrrev_b32_e32 v0, 8, v208
	v_and_b32_e32 v1, 15, v208
	v_lshl_add_u32 v0, v0, 6, v1
	v_bfe_u32 v1, v208, 6, 2
	v_bfe_u32 v2, v208, 4, 2
	v_lshlrev_b32_e32 v1, 6, v1
	v_lshl_add_u32 v1, v2, 4, v1
	v_lshl_add_u32 v138, v0, 9, v1
	s_branch .LBB0_215
.LBB0_214:
	v_cvt_pk_bf16_f32 v120, v120, v121
	v_cvt_pk_bf16_f32 v121, v122, v123
	v_cvt_pk_bf16_f32 v122, v116, v117
	v_cvt_pk_bf16_f32 v123, v118, v119
	v_cvt_pk_bf16_f32 v104, v104, v105
	v_cvt_pk_bf16_f32 v105, v106, v107
	v_cvt_pk_bf16_f32 v106, v100, v101
	v_cvt_pk_bf16_f32 v107, v102, v103
	v_cvt_pk_bf16_f32 v88, v88, v89
	v_cvt_pk_bf16_f32 v89, v90, v91
	v_cvt_pk_bf16_f32 v90, v84, v85
	v_cvt_pk_bf16_f32 v91, v86, v87
	v_cvt_pk_bf16_f32 v76, v76, v77
	v_cvt_pk_bf16_f32 v77, v78, v79
	v_cvt_pk_bf16_f32 v78, v72, v73
	v_cvt_pk_bf16_f32 v79, v74, v75
	v_cvt_pk_bf16_f32 v68, v68, v69
	v_cvt_pk_bf16_f32 v69, v70, v71
	v_cvt_pk_bf16_f32 v70, v64, v65
	v_cvt_pk_bf16_f32 v71, v66, v67
	v_cvt_pk_bf16_f32 v60, v60, v61
	v_cvt_pk_bf16_f32 v61, v62, v63
	v_cvt_pk_bf16_f32 v62, v56, v57
	v_cvt_pk_bf16_f32 v63, v58, v59
	v_cvt_pk_bf16_f32 v52, v52, v53
	v_cvt_pk_bf16_f32 v53, v54, v55
	v_cvt_pk_bf16_f32 v54, v48, v49
	v_cvt_pk_bf16_f32 v55, v50, v51
	v_cvt_pk_bf16_f32 v44, v44, v45
	v_cvt_pk_bf16_f32 v45, v46, v47
	v_cvt_pk_bf16_f32 v46, v40, v41
	v_cvt_pk_bf16_f32 v47, v42, v43
	v_cvt_pk_bf16_f32 v36, v36, v37
	v_cvt_pk_bf16_f32 v37, v38, v39
	v_cvt_pk_bf16_f32 v38, v32, v33
	v_cvt_pk_bf16_f32 v39, v34, v35
	v_cvt_pk_bf16_f32 v28, v28, v29
	v_cvt_pk_bf16_f32 v29, v30, v31
	v_cvt_pk_bf16_f32 v30, v24, v25
	v_cvt_pk_bf16_f32 v31, v26, v27
	v_cvt_pk_bf16_f32 v20, v20, v21
	v_cvt_pk_bf16_f32 v21, v22, v23
	v_cvt_pk_bf16_f32 v22, v16, v17
	v_cvt_pk_bf16_f32 v23, v18, v19
	v_cvt_pk_bf16_f32 v12, v12, v13
	v_cvt_pk_bf16_f32 v13, v14, v15
	v_cvt_pk_bf16_f32 v14, v8, v9
	v_cvt_pk_bf16_f32 v15, v10, v11
	v_cvt_pk_bf16_f32 v4, v4, v5
	v_cvt_pk_bf16_f32 v5, v6, v7
	v_cvt_pk_bf16_f32 v6, v0, v1
	v_cvt_pk_bf16_f32 v7, v2, v3
	s_add_u32 s78, s98, 0x0
	s_addc_u32 s79, s99, 0
	global_store_dwordx4 v138, v[120:123], s[78:79] offset:256 nt
	s_add_u32 s78, s98, 0x2000
	s_addc_u32 s79, s99, 0
	global_store_dwordx4 v138, v[104:107], s[78:79] offset:256 nt
	s_add_u32 s78, s98, 0x4000
	s_addc_u32 s79, s99, 0
	global_store_dwordx4 v138, v[88:91], s[78:79] offset:256 nt
	s_add_u32 s78, s98, 0x6000
	s_addc_u32 s79, s99, 0
	global_store_dwordx4 v138, v[76:79], s[78:79] nt
	s_add_u32 s78, s98, 0x6000
	s_addc_u32 s79, s99, 0
	global_store_dwordx4 v138, v[68:71], s[78:79] offset:256 nt
	s_add_u32 s78, s98, 0x10000
	s_addc_u32 s79, s99, 0
	global_store_dwordx4 v138, v[60:63], s[78:79] nt
	s_add_u32 s78, s98, 0x10000
	s_addc_u32 s79, s99, 0
	global_store_dwordx4 v138, v[52:55], s[78:79] offset:256 nt
	s_add_u32 s78, s98, 0x12000
	s_addc_u32 s79, s99, 0
	global_store_dwordx4 v138, v[44:47], s[78:79] nt
	s_add_u32 s78, s98, 0x12000
	s_addc_u32 s79, s99, 0
	global_store_dwordx4 v138, v[36:39], s[78:79] offset:256 nt
	s_add_u32 s78, s98, 0x14000
	s_addc_u32 s79, s99, 0
	global_store_dwordx4 v138, v[28:31], s[78:79] nt
	s_add_u32 s78, s98, 0x14000
	s_addc_u32 s79, s99, 0
	global_store_dwordx4 v138, v[20:23], s[78:79] offset:256 nt
	s_add_u32 s78, s98, 0x16000
	s_addc_u32 s79, s99, 0
	global_store_dwordx4 v138, v[12:15], s[78:79] nt
	s_add_u32 s78, s98, 0x16000
	s_addc_u32 s79, s99, 0
	global_store_dwordx4 v138, v[4:7], s[78:79] offset:256 nt
	s_branch .LBB0_225

.LBB0_223:
	s_add_i32 s46, s20, 2
	s_add_u32 s22, s18, 0x80
	s_addc_u32 s21, s19, 0
	s_add_i32 s47, 0, 0x10000
	v_add_u32_e32 v164, s47, v158
	ds_read_b128 v[160:163], v164
	ds_read_b128 v[176:179], v164 offset:1024
	ds_read_b128 v[180:183], v164 offset:2048
	ds_read_b128 v[184:187], v164 offset:3072
	s_cmp_eq_u32 s38, s20
	s_cselect_b32 s20, s8, s22
	s_cselect_b32 s21, s9, s21
	s_cselect_b32 s23, s11, s45
	s_cselect_b32 s22, s10, s44
	v_lshl_add_u64 v[164:165], s[18:19], 0, v[156:157]
	s_add_i32 m0, s29, 0xc000
	ds_read_b128 v[188:191], v159
	ds_read_b128 v[192:195], v159 offset:1024
	ds_read_b128 v[196:199], v159 offset:2048
	ds_read_b128 v[200:203], v159 offset:3072
	ds_read_b128 v[204:207], v159 offset:4096
	ds_read_b128 v[218:221], v159 offset:5120
	ds_read_b128 v[224:227], v159 offset:6144
	ds_read_b128 v[228:231], v159 offset:7168
	global_load_lds_dwordx4 v[164:165], off
	v_lshl_add_u64 v[164:165], s[18:19], 0, v[154:155]
	s_add_i32 m0, s29, 0xe000
	s_nop 0
	global_load_lds_dwordx4 v[164:165], off
	s_waitcnt lgkmcnt(8)
	s_barrier
	s_waitcnt lgkmcnt(0)
	s_setprio 1
	s_waitcnt lgkmcnt(0)
	v_mfma_f32_16x16x32_bf16 v[124:127], v[160:163], v[188:191], v[124:127]
	v_mfma_f32_16x16x32_bf16 v[128:131], v[180:183], v[188:191], v[128:131]
	v_mfma_f32_16x16x32_bf16 v[112:115], v[160:163], v[196:199], v[112:115]
	v_mfma_f32_16x16x32_bf16 v[108:111], v[180:183], v[196:199], v[108:111]
	v_mfma_f32_16x16x32_bf16 v[96:99], v[160:163], v[204:207], v[96:99]
	v_mfma_f32_16x16x32_bf16 v[92:95], v[180:183], v[204:207], v[92:95]
	v_mfma_f32_16x16x32_bf16 v[76:79], v[160:163], v[224:227], v[76:79]
	v_mfma_f32_16x16x32_bf16 v[72:75], v[180:183], v[224:227], v[72:75]
	v_mfma_f32_16x16x32_bf16 v[124:127], v[176:179], v[192:195], v[124:127]
	v_mfma_f32_16x16x32_bf16 v[128:131], v[184:187], v[192:195], v[128:131]
	v_mfma_f32_16x16x32_bf16 v[112:115], v[176:179], v[200:203], v[112:115]
	v_mfma_f32_16x16x32_bf16 v[108:111], v[184:187], v[200:203], v[108:111]
	v_mfma_f32_16x16x32_bf16 v[96:99], v[176:179], v[218:221], v[96:99]
	v_mfma_f32_16x16x32_bf16 v[92:95], v[184:187], v[218:221], v[92:95]
	v_mfma_f32_16x16x32_bf16 v[76:79], v[176:179], v[228:231], v[76:79]
	v_mfma_f32_16x16x32_bf16 v[72:75], v[184:187], v[228:231], v[72:75]
	s_setprio 0
	s_barrier
	s_add_i32 s48, 0, 0x14000
	v_add_u32_e32 v164, s48, v158
	s_add_i32 s47, s47, s28
	ds_read_b128 v[232:235], v164
	ds_read_b128 v[236:239], v164 offset:1024
	ds_read_b128 v[240:243], v164 offset:2048
	ds_read_b128 v[244:247], v164 offset:3072
	v_lshl_add_u64 v[164:165], s[22:23], 0, v[166:167]
	s_mov_b32 m0, s47
	v_lshl_add_u64 v[248:249], s[22:23], 0, v[132:133]
	global_load_lds_dwordx4 v[164:165], off
	s_add_i32 m0, s47, 0x2000
	s_nop 0
	global_load_lds_dwordx4 v[248:249], off
	s_barrier
	s_waitcnt lgkmcnt(0)
	s_setprio 1
	s_waitcnt lgkmcnt(0)
	v_mfma_f32_16x16x32_bf16 v[120:123], v[232:235], v[188:191], v[120:123]
	v_mfma_f32_16x16x32_bf16 v[116:119], v[240:243], v[188:191], v[116:119]
	v_mfma_f32_16x16x32_bf16 v[104:107], v[232:235], v[196:199], v[104:107]
	v_mfma_f32_16x16x32_bf16 v[100:103], v[240:243], v[196:199], v[100:103]
	v_mfma_f32_16x16x32_bf16 v[88:91], v[232:235], v[204:207], v[88:91]
	v_mfma_f32_16x16x32_bf16 v[84:87], v[240:243], v[204:207], v[84:87]
	v_mfma_f32_16x16x32_bf16 v[68:71], v[232:235], v[224:227], v[68:71]
	v_mfma_f32_16x16x32_bf16 v[64:67], v[240:243], v[224:227], v[64:67]
	v_mfma_f32_16x16x32_bf16 v[120:123], v[236:239], v[192:195], v[120:123]
	v_mfma_f32_16x16x32_bf16 v[116:119], v[244:247], v[192:195], v[116:119]
	v_mfma_f32_16x16x32_bf16 v[104:107], v[236:239], v[200:203], v[104:107]
	v_mfma_f32_16x16x32_bf16 v[100:103], v[244:247], v[200:203], v[100:103]
	v_mfma_f32_16x16x32_bf16 v[88:91], v[236:239], v[218:221], v[88:91]
	v_mfma_f32_16x16x32_bf16 v[84:87], v[244:247], v[218:221], v[84:87]
	v_mfma_f32_16x16x32_bf16 v[68:71], v[236:239], v[228:231], v[68:71]
	v_mfma_f32_16x16x32_bf16 v[64:67], v[244:247], v[228:231], v[64:67]
	s_setprio 0
	s_mov_b32 m0, s29
	v_lshl_add_u64 v[250:251], s[20:21], 0, v[136:137]
	s_barrier
	ds_read_b128 v[188:191], v159 offset:16384
	ds_read_b128 v[192:195], v159 offset:17408
	ds_read_b128 v[196:199], v159 offset:18432
	ds_read_b128 v[200:203], v159 offset:19456
	ds_read_b128 v[204:207], v159 offset:20480
	ds_read_b128 v[218:221], v159 offset:21504
	ds_read_b128 v[224:227], v159 offset:22528
	ds_read_b128 v[228:231], v159 offset:23552
	global_load_lds_dwordx4 v[250:251], off
	v_lshl_add_u64 v[210:211], s[20:21], 0, v[134:135]
	s_mov_b32 m0, s30
	s_nop 0
	global_load_lds_dwordx4 v[210:211], off
	s_barrier
	s_waitcnt lgkmcnt(0)
	s_setprio 1
	s_waitcnt lgkmcnt(0)
	v_mfma_f32_16x16x32_bf16 v[60:63], v[160:163], v[188:191], v[60:63]
	v_mfma_f32_16x16x32_bf16 v[56:59], v[180:183], v[188:191], v[56:59]
	v_mfma_f32_16x16x32_bf16 v[44:47], v[160:163], v[196:199], v[44:47]
	v_mfma_f32_16x16x32_bf16 v[40:43], v[180:183], v[196:199], v[40:43]
	v_mfma_f32_16x16x32_bf16 v[28:31], v[160:163], v[204:207], v[28:31]
	v_mfma_f32_16x16x32_bf16 v[24:27], v[180:183], v[204:207], v[24:27]
	v_mfma_f32_16x16x32_bf16 v[12:15], v[160:163], v[224:227], v[12:15]
	v_mfma_f32_16x16x32_bf16 v[8:11], v[180:183], v[224:227], v[8:11]
	v_mfma_f32_16x16x32_bf16 v[60:63], v[176:179], v[192:195], v[60:63]
	v_mfma_f32_16x16x32_bf16 v[56:59], v[184:187], v[192:195], v[56:59]
	v_mfma_f32_16x16x32_bf16 v[44:47], v[176:179], v[200:203], v[44:47]
	v_mfma_f32_16x16x32_bf16 v[40:43], v[184:187], v[200:203], v[40:43]
	v_mfma_f32_16x16x32_bf16 v[28:31], v[176:179], v[218:221], v[28:31]
	v_mfma_f32_16x16x32_bf16 v[24:27], v[184:187], v[218:221], v[24:27]
	v_mfma_f32_16x16x32_bf16 v[12:15], v[176:179], v[228:231], v[12:15]
	v_mfma_f32_16x16x32_bf16 v[8:11], v[184:187], v[228:231], v[8:11]
	s_setprio 0
	s_barrier
	s_add_u32 s22, s22, s12
	s_addc_u32 s23, s23, s13
	s_add_i32 s47, s48, s28
	v_lshl_add_u64 v[170:171], s[22:23], 0, v[166:167]
	s_mov_b32 m0, s47
	v_lshl_add_u64 v[172:173], s[22:23], 0, v[132:133]
	global_load_lds_dwordx4 v[170:171], off
	s_add_i32 m0, s47, 0x2000
	s_nop 0
	global_load_lds_dwordx4 v[172:173], off
	s_waitcnt vmcnt(6)
	s_barrier
	s_setprio 1
	v_mfma_f32_16x16x32_bf16 v[52:55], v[232:235], v[188:191], v[52:55]
	v_mfma_f32_16x16x32_bf16 v[48:51], v[240:243], v[188:191], v[48:51]
	v_mfma_f32_16x16x32_bf16 v[36:39], v[232:235], v[196:199], v[36:39]
	v_mfma_f32_16x16x32_bf16 v[32:35], v[240:243], v[196:199], v[32:35]
	v_mfma_f32_16x16x32_bf16 v[20:23], v[232:235], v[204:207], v[20:23]
	v_mfma_f32_16x16x32_bf16 v[16:19], v[240:243], v[204:207], v[16:19]
	v_mfma_f32_16x16x32_bf16 v[4:7], v[232:235], v[224:227], v[4:7]
	v_mfma_f32_16x16x32_bf16 v[0:3], v[240:243], v[224:227], v[0:3]
	v_mfma_f32_16x16x32_bf16 v[52:55], v[236:239], v[192:195], v[52:55]
	v_mfma_f32_16x16x32_bf16 v[48:51], v[244:247], v[192:195], v[48:51]
	v_mfma_f32_16x16x32_bf16 v[36:39], v[236:239], v[200:203], v[36:39]
	v_mfma_f32_16x16x32_bf16 v[32:35], v[244:247], v[200:203], v[32:35]
	v_mfma_f32_16x16x32_bf16 v[20:23], v[236:239], v[218:221], v[20:23]
	v_mfma_f32_16x16x32_bf16 v[16:19], v[244:247], v[218:221], v[16:19]
	v_mfma_f32_16x16x32_bf16 v[4:7], v[236:239], v[228:231], v[4:7]
	v_mfma_f32_16x16x32_bf16 v[0:3], v[244:247], v[228:231], v[0:3]
	s_setprio 0
	s_add_i32 s22, 0, 0x18000
	v_add_u32_e32 v169, s22, v158
	s_barrier
	ds_read_b128 v[160:163], v169
	ds_read_b128 v[176:179], v169 offset:1024
	ds_read_b128 v[180:183], v169 offset:2048
	ds_read_b128 v[184:187], v169 offset:3072
	s_add_u32 s20, s20, s12
	s_addc_u32 s21, s21, s13
	s_mov_b32 m0, s31
	v_lshl_add_u64 v[232:233], s[20:21], 0, v[136:137]
	ds_read_b128 v[188:191], v159 offset:32768
	ds_read_b128 v[192:195], v159 offset:33792
	ds_read_b128 v[196:199], v159 offset:34816
	ds_read_b128 v[200:203], v159 offset:35840
	ds_read_b128 v[204:207], v159 offset:36864
	ds_read_b128 v[218:221], v159 offset:37888
	ds_read_b128 v[224:227], v159 offset:38912
	ds_read_b128 v[228:231], v159 offset:39936
	global_load_lds_dwordx4 v[232:233], off
	v_lshl_add_u64 v[232:233], s[20:21], 0, v[134:135]
	s_mov_b32 m0, s34
	s_nop 0
	global_load_lds_dwordx4 v[232:233], off
	s_waitcnt lgkmcnt(8)
	s_barrier
	s_waitcnt lgkmcnt(0)
	s_setprio 1
	s_waitcnt lgkmcnt(0)
	v_mfma_f32_16x16x32_bf16 v[124:127], v[160:163], v[188:191], v[124:127]
	v_mfma_f32_16x16x32_bf16 v[128:131], v[180:183], v[188:191], v[128:131]
	v_mfma_f32_16x16x32_bf16 v[112:115], v[160:163], v[196:199], v[112:115]
	v_mfma_f32_16x16x32_bf16 v[108:111], v[180:183], v[196:199], v[108:111]
	v_mfma_f32_16x16x32_bf16 v[96:99], v[160:163], v[204:207], v[96:99]
	v_mfma_f32_16x16x32_bf16 v[92:95], v[180:183], v[204:207], v[92:95]
	v_mfma_f32_16x16x32_bf16 v[76:79], v[160:163], v[224:227], v[76:79]
	v_mfma_f32_16x16x32_bf16 v[72:75], v[180:183], v[224:227], v[72:75]
	v_mfma_f32_16x16x32_bf16 v[124:127], v[176:179], v[192:195], v[124:127]
	v_mfma_f32_16x16x32_bf16 v[128:131], v[184:187], v[192:195], v[128:131]
	v_mfma_f32_16x16x32_bf16 v[112:115], v[176:179], v[200:203], v[112:115]
	v_mfma_f32_16x16x32_bf16 v[108:111], v[184:187], v[200:203], v[108:111]
	v_mfma_f32_16x16x32_bf16 v[96:99], v[176:179], v[218:221], v[96:99]
	v_mfma_f32_16x16x32_bf16 v[92:95], v[184:187], v[218:221], v[92:95]
	v_mfma_f32_16x16x32_bf16 v[76:79], v[176:179], v[228:231], v[76:79]
	v_mfma_f32_16x16x32_bf16 v[72:75], v[184:187], v[228:231], v[72:75]
	s_setprio 0
	s_barrier
	s_add_i32 s20, 0, 0x1c000
	s_add_i32 s21, s22, s28
	v_add_u32_e32 v169, s20, v158
	v_lshl_add_u64 v[164:165], v[164:165], 0, s[88:89]
	s_mov_b32 m0, s21
	ds_read_b128 v[232:235], v169
	ds_read_b128 v[236:239], v169 offset:1024
	ds_read_b128 v[240:243], v169 offset:2048
	ds_read_b128 v[244:247], v169 offset:3072
	global_load_lds_dwordx4 v[164:165], off
	v_lshl_add_u64 v[164:165], v[248:249], 0, s[88:89]
	s_add_i32 m0, s21, 0x2000
	s_nop 0
	global_load_lds_dwordx4 v[164:165], off
	s_barrier
	s_waitcnt lgkmcnt(0)
	s_setprio 1
	s_waitcnt lgkmcnt(0)
	v_mfma_f32_16x16x32_bf16 v[120:123], v[232:235], v[188:191], v[120:123]
	v_mfma_f32_16x16x32_bf16 v[116:119], v[240:243], v[188:191], v[116:119]
	v_mfma_f32_16x16x32_bf16 v[104:107], v[232:235], v[196:199], v[104:107]
	v_mfma_f32_16x16x32_bf16 v[100:103], v[240:243], v[196:199], v[100:103]
	v_mfma_f32_16x16x32_bf16 v[88:91], v[232:235], v[204:207], v[88:91]
	v_mfma_f32_16x16x32_bf16 v[84:87], v[240:243], v[204:207], v[84:87]
	v_mfma_f32_16x16x32_bf16 v[68:71], v[232:235], v[224:227], v[68:71]
	v_mfma_f32_16x16x32_bf16 v[64:67], v[240:243], v[224:227], v[64:67]
	v_mfma_f32_16x16x32_bf16 v[120:123], v[236:239], v[192:195], v[120:123]
	v_mfma_f32_16x16x32_bf16 v[116:119], v[244:247], v[192:195], v[116:119]
	v_mfma_f32_16x16x32_bf16 v[104:107], v[236:239], v[200:203], v[104:107]
	v_mfma_f32_16x16x32_bf16 v[100:103], v[244:247], v[200:203], v[100:103]
	v_mfma_f32_16x16x32_bf16 v[88:91], v[236:239], v[218:221], v[88:91]
	v_mfma_f32_16x16x32_bf16 v[84:87], v[244:247], v[218:221], v[84:87]
	v_mfma_f32_16x16x32_bf16 v[68:71], v[236:239], v[228:231], v[68:71]
	v_mfma_f32_16x16x32_bf16 v[64:67], v[244:247], v[228:231], v[64:67]
	s_setprio 0
	s_mov_b32 m0, s36
	v_lshl_add_u64 v[164:165], v[250:251], 0, s[88:89]
	s_barrier
	ds_read_b128 v[188:191], v159 offset:49152
	ds_read_b128 v[192:195], v159 offset:50176
	ds_read_b128 v[196:199], v159 offset:51200
	ds_read_b128 v[200:203], v159 offset:52224
	ds_read_b128 v[204:207], v159 offset:53248
	ds_read_b128 v[218:221], v159 offset:54272
	ds_read_b128 v[224:227], v159 offset:55296
	ds_read_b128 v[228:231], v159 offset:56320
	global_load_lds_dwordx4 v[164:165], off
	v_lshl_add_u64 v[164:165], v[210:211], 0, s[88:89]
	s_mov_b32 m0, s37
	s_nop 0
	global_load_lds_dwordx4 v[164:165], off
	s_barrier
	s_waitcnt lgkmcnt(0)
	s_setprio 1
	s_waitcnt lgkmcnt(0)
	v_mfma_f32_16x16x32_bf16 v[60:63], v[160:163], v[188:191], v[60:63]
	v_mfma_f32_16x16x32_bf16 v[56:59], v[180:183], v[188:191], v[56:59]
	v_mfma_f32_16x16x32_bf16 v[44:47], v[160:163], v[196:199], v[44:47]
	v_mfma_f32_16x16x32_bf16 v[40:43], v[180:183], v[196:199], v[40:43]
	v_mfma_f32_16x16x32_bf16 v[28:31], v[160:163], v[204:207], v[28:31]
	v_mfma_f32_16x16x32_bf16 v[24:27], v[180:183], v[204:207], v[24:27]
	v_mfma_f32_16x16x32_bf16 v[12:15], v[160:163], v[224:227], v[12:15]
	v_mfma_f32_16x16x32_bf16 v[8:11], v[180:183], v[224:227], v[8:11]
	v_mfma_f32_16x16x32_bf16 v[60:63], v[176:179], v[192:195], v[60:63]
	v_mfma_f32_16x16x32_bf16 v[56:59], v[184:187], v[192:195], v[56:59]
	v_mfma_f32_16x16x32_bf16 v[44:47], v[176:179], v[200:203], v[44:47]
	v_mfma_f32_16x16x32_bf16 v[40:43], v[184:187], v[200:203], v[40:43]
	v_mfma_f32_16x16x32_bf16 v[28:31], v[176:179], v[218:221], v[28:31]
	v_mfma_f32_16x16x32_bf16 v[24:27], v[184:187], v[218:221], v[24:27]
	v_mfma_f32_16x16x32_bf16 v[12:15], v[176:179], v[228:231], v[12:15]
	v_mfma_f32_16x16x32_bf16 v[8:11], v[184:187], v[228:231], v[8:11]
	s_setprio 0
	s_barrier
	s_add_i32 s20, s20, s28
	v_lshl_add_u64 v[160:161], v[170:171], 0, s[88:89]
	s_mov_b32 m0, s20
	s_nop 0
	global_load_lds_dwordx4 v[160:161], off
	v_lshl_add_u64 v[160:161], v[172:173], 0, s[88:89]
	s_add_i32 m0, s20, 0x2000
	s_nop 0
	global_load_lds_dwordx4 v[160:161], off
	s_waitcnt vmcnt(6)
	s_barrier
	s_setprio 1
	v_mfma_f32_16x16x32_bf16 v[52:55], v[232:235], v[188:191], v[52:55]
	v_mfma_f32_16x16x32_bf16 v[48:51], v[240:243], v[188:191], v[48:51]
	v_mfma_f32_16x16x32_bf16 v[36:39], v[232:235], v[196:199], v[36:39]
	v_mfma_f32_16x16x32_bf16 v[32:35], v[240:243], v[196:199], v[32:35]
	v_mfma_f32_16x16x32_bf16 v[20:23], v[232:235], v[204:207], v[20:23]
	v_mfma_f32_16x16x32_bf16 v[16:19], v[240:243], v[204:207], v[16:19]
	v_mfma_f32_16x16x32_bf16 v[4:7], v[232:235], v[224:227], v[4:7]
	v_mfma_f32_16x16x32_bf16 v[0:3], v[240:243], v[224:227], v[0:3]
	v_mfma_f32_16x16x32_bf16 v[52:55], v[236:239], v[192:195], v[52:55]
	v_mfma_f32_16x16x32_bf16 v[48:51], v[244:247], v[192:195], v[48:51]
	v_mfma_f32_16x16x32_bf16 v[36:39], v[236:239], v[200:203], v[36:39]
	v_mfma_f32_16x16x32_bf16 v[32:35], v[244:247], v[200:203], v[32:35]
	v_mfma_f32_16x16x32_bf16 v[20:23], v[236:239], v[218:221], v[20:23]
	v_mfma_f32_16x16x32_bf16 v[16:19], v[244:247], v[218:221], v[16:19]
	v_mfma_f32_16x16x32_bf16 v[4:7], v[236:239], v[228:231], v[4:7]
	v_mfma_f32_16x16x32_bf16 v[0:3], v[244:247], v[228:231], v[0:3]
	s_setprio 0
	s_add_u32 s44, s44, 0x100
	s_addc_u32 s45, s45, 0
	s_add_u32 s18, s18, 0x100
	s_addc_u32 s19, s19, 0
	s_cmp_ge_i32 s46, s38
	s_mov_b32 s20, s46
	s_barrier
	s_cbranch_scc0 .LBB0_223
.Lp2_last:
	s_mul_i32 s49, s43, 49
	s_add_i32 s49, s49, s42
	s_lshl_b32 s49, s49, 17
	s_add_u32 s98, s60, 0x74c2800
	s_addc_u32 s99, s61, 0
	s_add_u32 s98, s98, s49
	s_addc_u32 s99, s99, 0
	s_add_i32 s46, s20, 2
	s_add_u32 s22, s18, 0x80
	s_addc_u32 s21, s19, 0
	s_add_i32 s47, 0, 0x10000
	v_add_u32_e32 v164, s47, v158
	ds_read_b128 v[160:163], v164
	ds_read_b128 v[176:179], v164 offset:1024
	ds_read_b128 v[180:183], v164 offset:2048
	ds_read_b128 v[184:187], v164 offset:3072
	s_cmp_eq_u32 s38, s20
	s_cselect_b32 s20, s8, s22
	s_cselect_b32 s21, s9, s21
	s_cselect_b32 s23, s11, s45
	s_cselect_b32 s22, s10, s44
	v_lshl_add_u64 v[164:165], s[18:19], 0, v[156:157]
	s_add_i32 m0, s29, 0xc000
	ds_read_b128 v[188:191], v159
	ds_read_b128 v[192:195], v159 offset:1024
	ds_read_b128 v[196:199], v159 offset:2048
	ds_read_b128 v[200:203], v159 offset:3072
	ds_read_b128 v[204:207], v159 offset:4096
	ds_read_b128 v[218:221], v159 offset:5120
	ds_read_b128 v[224:227], v159 offset:6144
	ds_read_b128 v[228:231], v159 offset:7168
	global_load_lds_dwordx4 v[164:165], off
	v_lshl_add_u64 v[164:165], s[18:19], 0, v[154:155]
	s_add_i32 m0, s29, 0xe000
	s_nop 0
	global_load_lds_dwordx4 v[164:165], off
	s_waitcnt lgkmcnt(8)
	s_barrier
	s_waitcnt lgkmcnt(0)
	s_setprio 1
	s_waitcnt lgkmcnt(0)
	v_mfma_f32_16x16x32_bf16 v[124:127], v[160:163], v[188:191], v[124:127]
	v_mfma_f32_16x16x32_bf16 v[128:131], v[180:183], v[188:191], v[128:131]
	v_mfma_f32_16x16x32_bf16 v[112:115], v[160:163], v[196:199], v[112:115]
	v_mfma_f32_16x16x32_bf16 v[108:111], v[180:183], v[196:199], v[108:111]
	v_mfma_f32_16x16x32_bf16 v[96:99], v[160:163], v[204:207], v[96:99]
	v_mfma_f32_16x16x32_bf16 v[92:95], v[180:183], v[204:207], v[92:95]
	v_mfma_f32_16x16x32_bf16 v[76:79], v[160:163], v[224:227], v[76:79]
	v_mfma_f32_16x16x32_bf16 v[72:75], v[180:183], v[224:227], v[72:75]
	v_mfma_f32_16x16x32_bf16 v[124:127], v[176:179], v[192:195], v[124:127]
	v_mfma_f32_16x16x32_bf16 v[128:131], v[184:187], v[192:195], v[128:131]
	v_mfma_f32_16x16x32_bf16 v[112:115], v[176:179], v[200:203], v[112:115]
	v_mfma_f32_16x16x32_bf16 v[108:111], v[184:187], v[200:203], v[108:111]
	v_mfma_f32_16x16x32_bf16 v[96:99], v[176:179], v[218:221], v[96:99]
	v_mfma_f32_16x16x32_bf16 v[92:95], v[184:187], v[218:221], v[92:95]
	v_mfma_f32_16x16x32_bf16 v[76:79], v[176:179], v[228:231], v[76:79]
	v_mfma_f32_16x16x32_bf16 v[72:75], v[184:187], v[228:231], v[72:75]
	s_setprio 0
	s_barrier
	s_add_i32 s48, 0, 0x14000
	v_add_u32_e32 v164, s48, v158
	s_add_i32 s47, s47, s28
	ds_read_b128 v[232:235], v164
	ds_read_b128 v[236:239], v164 offset:1024
	ds_read_b128 v[240:243], v164 offset:2048
	ds_read_b128 v[244:247], v164 offset:3072
	v_lshl_add_u64 v[164:165], s[22:23], 0, v[166:167]
	s_mov_b32 m0, s47
	v_lshl_add_u64 v[248:249], s[22:23], 0, v[132:133]
	global_load_lds_dwordx4 v[164:165], off
	s_add_i32 m0, s47, 0x2000
	s_nop 0
	global_load_lds_dwordx4 v[248:249], off
	s_barrier
	s_waitcnt lgkmcnt(0)
	s_setprio 1
	s_waitcnt lgkmcnt(0)
	v_mfma_f32_16x16x32_bf16 v[120:123], v[232:235], v[188:191], v[120:123]
	v_mfma_f32_16x16x32_bf16 v[116:119], v[240:243], v[188:191], v[116:119]
	v_mfma_f32_16x16x32_bf16 v[104:107], v[232:235], v[196:199], v[104:107]
	v_mfma_f32_16x16x32_bf16 v[100:103], v[240:243], v[196:199], v[100:103]
	v_mfma_f32_16x16x32_bf16 v[88:91], v[232:235], v[204:207], v[88:91]
	v_mfma_f32_16x16x32_bf16 v[84:87], v[240:243], v[204:207], v[84:87]
	v_mfma_f32_16x16x32_bf16 v[68:71], v[232:235], v[224:227], v[68:71]
	v_mfma_f32_16x16x32_bf16 v[64:67], v[240:243], v[224:227], v[64:67]
	v_mfma_f32_16x16x32_bf16 v[120:123], v[236:239], v[192:195], v[120:123]
	v_mfma_f32_16x16x32_bf16 v[116:119], v[244:247], v[192:195], v[116:119]
	v_mfma_f32_16x16x32_bf16 v[104:107], v[236:239], v[200:203], v[104:107]
	v_mfma_f32_16x16x32_bf16 v[100:103], v[244:247], v[200:203], v[100:103]
	v_mfma_f32_16x16x32_bf16 v[88:91], v[236:239], v[218:221], v[88:91]
	v_mfma_f32_16x16x32_bf16 v[84:87], v[244:247], v[218:221], v[84:87]
	v_mfma_f32_16x16x32_bf16 v[68:71], v[236:239], v[228:231], v[68:71]
	v_mfma_f32_16x16x32_bf16 v[64:67], v[244:247], v[228:231], v[64:67]
	s_setprio 0
	s_mov_b32 m0, s29
	v_lshl_add_u64 v[250:251], s[20:21], 0, v[136:137]
	s_barrier
	ds_read_b128 v[188:191], v159 offset:16384
	ds_read_b128 v[192:195], v159 offset:17408
	ds_read_b128 v[196:199], v159 offset:18432
	ds_read_b128 v[200:203], v159 offset:19456
	ds_read_b128 v[204:207], v159 offset:20480
	ds_read_b128 v[218:221], v159 offset:21504
	ds_read_b128 v[224:227], v159 offset:22528
	ds_read_b128 v[228:231], v159 offset:23552
	global_load_lds_dwordx4 v[250:251], off
	v_lshl_add_u64 v[210:211], s[20:21], 0, v[134:135]
	s_mov_b32 m0, s30
	s_nop 0
	global_load_lds_dwordx4 v[210:211], off
	s_barrier
	s_waitcnt lgkmcnt(0)
	s_setprio 1
	s_waitcnt lgkmcnt(0)
	v_mfma_f32_16x16x32_bf16 v[60:63], v[160:163], v[188:191], v[60:63]
	v_mfma_f32_16x16x32_bf16 v[56:59], v[180:183], v[188:191], v[56:59]
	v_mfma_f32_16x16x32_bf16 v[44:47], v[160:163], v[196:199], v[44:47]
	v_mfma_f32_16x16x32_bf16 v[40:43], v[180:183], v[196:199], v[40:43]
	v_mfma_f32_16x16x32_bf16 v[28:31], v[160:163], v[204:207], v[28:31]
	v_mfma_f32_16x16x32_bf16 v[24:27], v[180:183], v[204:207], v[24:27]
	v_mfma_f32_16x16x32_bf16 v[12:15], v[160:163], v[224:227], v[12:15]
	v_mfma_f32_16x16x32_bf16 v[8:11], v[180:183], v[224:227], v[8:11]
	v_mfma_f32_16x16x32_bf16 v[60:63], v[176:179], v[192:195], v[60:63]
	v_mfma_f32_16x16x32_bf16 v[56:59], v[184:187], v[192:195], v[56:59]
	v_mfma_f32_16x16x32_bf16 v[44:47], v[176:179], v[200:203], v[44:47]
	v_mfma_f32_16x16x32_bf16 v[40:43], v[184:187], v[200:203], v[40:43]
	v_mfma_f32_16x16x32_bf16 v[28:31], v[176:179], v[218:221], v[28:31]
	v_mfma_f32_16x16x32_bf16 v[24:27], v[184:187], v[218:221], v[24:27]
	v_mfma_f32_16x16x32_bf16 v[12:15], v[176:179], v[228:231], v[12:15]
	v_mfma_f32_16x16x32_bf16 v[8:11], v[184:187], v[228:231], v[8:11]
	s_setprio 0
	s_barrier
	s_add_u32 s22, s22, s12
	s_addc_u32 s23, s23, s13
	s_add_i32 s47, s48, s28
	v_lshl_add_u64 v[170:171], s[22:23], 0, v[166:167]
	s_mov_b32 m0, s47
	v_lshl_add_u64 v[172:173], s[22:23], 0, v[132:133]
	global_load_lds_dwordx4 v[170:171], off
	s_add_i32 m0, s47, 0x2000
	s_nop 0
	global_load_lds_dwordx4 v[172:173], off
	s_waitcnt vmcnt(6)
	s_barrier
	s_setprio 1
	v_mfma_f32_16x16x32_bf16 v[52:55], v[232:235], v[188:191], v[52:55]
	v_mfma_f32_16x16x32_bf16 v[48:51], v[240:243], v[188:191], v[48:51]
	v_mfma_f32_16x16x32_bf16 v[36:39], v[232:235], v[196:199], v[36:39]
	v_mfma_f32_16x16x32_bf16 v[32:35], v[240:243], v[196:199], v[32:35]
	v_mfma_f32_16x16x32_bf16 v[20:23], v[232:235], v[204:207], v[20:23]
	v_mfma_f32_16x16x32_bf16 v[16:19], v[240:243], v[204:207], v[16:19]
	v_mfma_f32_16x16x32_bf16 v[4:7], v[232:235], v[224:227], v[4:7]
	v_mfma_f32_16x16x32_bf16 v[0:3], v[240:243], v[224:227], v[0:3]
	v_mfma_f32_16x16x32_bf16 v[52:55], v[236:239], v[192:195], v[52:55]
	v_mfma_f32_16x16x32_bf16 v[48:51], v[244:247], v[192:195], v[48:51]
	v_mfma_f32_16x16x32_bf16 v[36:39], v[236:239], v[200:203], v[36:39]
	v_mfma_f32_16x16x32_bf16 v[32:35], v[244:247], v[200:203], v[32:35]
	v_mfma_f32_16x16x32_bf16 v[20:23], v[236:239], v[218:221], v[20:23]
	v_mfma_f32_16x16x32_bf16 v[16:19], v[244:247], v[218:221], v[16:19]
	v_mfma_f32_16x16x32_bf16 v[4:7], v[236:239], v[228:231], v[4:7]
	v_mfma_f32_16x16x32_bf16 v[0:3], v[244:247], v[228:231], v[0:3]
	s_setprio 0
	s_add_i32 s22, 0, 0x18000
	v_add_u32_e32 v169, s22, v158
	s_barrier
	ds_read_b128 v[160:163], v169
	ds_read_b128 v[176:179], v169 offset:1024
	ds_read_b128 v[180:183], v169 offset:2048
	ds_read_b128 v[184:187], v169 offset:3072
	s_add_u32 s20, s20, s12
	s_addc_u32 s21, s21, s13
	s_mov_b32 m0, s31
	v_lshl_add_u64 v[232:233], s[20:21], 0, v[136:137]
	ds_read_b128 v[188:191], v159 offset:32768
	ds_read_b128 v[192:195], v159 offset:33792
	ds_read_b128 v[196:199], v159 offset:34816
	ds_read_b128 v[200:203], v159 offset:35840
	ds_read_b128 v[204:207], v159 offset:36864
	ds_read_b128 v[218:221], v159 offset:37888
	ds_read_b128 v[224:227], v159 offset:38912
	ds_read_b128 v[228:231], v159 offset:39936
	global_load_lds_dwordx4 v[232:233], off
	v_lshl_add_u64 v[232:233], s[20:21], 0, v[134:135]
	s_mov_b32 m0, s34
	s_nop 0
	global_load_lds_dwordx4 v[232:233], off
	s_waitcnt lgkmcnt(8)
	s_barrier
	s_waitcnt lgkmcnt(0)
	s_setprio 1
	s_waitcnt lgkmcnt(0)
	v_mfma_f32_16x16x32_bf16 v[124:127], v[160:163], v[188:191], v[124:127]
	v_mfma_f32_16x16x32_bf16 v[128:131], v[180:183], v[188:191], v[128:131]
	v_mfma_f32_16x16x32_bf16 v[112:115], v[160:163], v[196:199], v[112:115]
	v_mfma_f32_16x16x32_bf16 v[108:111], v[180:183], v[196:199], v[108:111]
	v_mfma_f32_16x16x32_bf16 v[96:99], v[160:163], v[204:207], v[96:99]
	v_mfma_f32_16x16x32_bf16 v[92:95], v[180:183], v[204:207], v[92:95]
	v_mfma_f32_16x16x32_bf16 v[76:79], v[160:163], v[224:227], v[76:79]
	v_mfma_f32_16x16x32_bf16 v[72:75], v[180:183], v[224:227], v[72:75]
	v_mfma_f32_16x16x32_bf16 v[124:127], v[176:179], v[192:195], v[124:127]
	v_mfma_f32_16x16x32_bf16 v[128:131], v[184:187], v[192:195], v[128:131]
	v_mfma_f32_16x16x32_bf16 v[112:115], v[176:179], v[200:203], v[112:115]
	v_mfma_f32_16x16x32_bf16 v[108:111], v[184:187], v[200:203], v[108:111]
	v_mfma_f32_16x16x32_bf16 v[96:99], v[176:179], v[218:221], v[96:99]
	v_mfma_f32_16x16x32_bf16 v[92:95], v[184:187], v[218:221], v[92:95]
	v_mfma_f32_16x16x32_bf16 v[76:79], v[176:179], v[228:231], v[76:79]
	v_mfma_f32_16x16x32_bf16 v[72:75], v[184:187], v[228:231], v[72:75]
	s_setprio 0
	s_barrier
	s_add_i32 s20, 0, 0x1c000
	s_add_i32 s21, s22, s28
	v_add_u32_e32 v169, s20, v158
	v_lshl_add_u64 v[164:165], v[164:165], 0, s[88:89]
	s_mov_b32 m0, s21
	ds_read_b128 v[232:235], v169
	ds_read_b128 v[236:239], v169 offset:1024
	ds_read_b128 v[240:243], v169 offset:2048
	ds_read_b128 v[244:247], v169 offset:3072
	global_load_lds_dwordx4 v[164:165], off
	v_lshl_add_u64 v[164:165], v[248:249], 0, s[88:89]
	s_add_i32 m0, s21, 0x2000
	s_nop 0
	global_load_lds_dwordx4 v[164:165], off
	v_cvt_pk_bf16_f32 v124, v124, v125
	v_cvt_pk_bf16_f32 v125, v126, v127
	v_cvt_pk_bf16_f32 v126, v128, v129
	v_cvt_pk_bf16_f32 v127, v130, v131
	s_add_u32 s78, s98, 0x0
	s_addc_u32 s79, s99, 0
	global_store_dwordx4 v138, v[124:127], s[78:79] nt
	s_barrier
	s_waitcnt lgkmcnt(0)
	s_setprio 1
	s_waitcnt lgkmcnt(0)
	v_mfma_f32_16x16x32_bf16 v[120:123], v[232:235], v[188:191], v[120:123]
	v_mfma_f32_16x16x32_bf16 v[116:119], v[240:243], v[188:191], v[116:119]
	v_mfma_f32_16x16x32_bf16 v[104:107], v[232:235], v[196:199], v[104:107]
	v_mfma_f32_16x16x32_bf16 v[100:103], v[240:243], v[196:199], v[100:103]
	v_mfma_f32_16x16x32_bf16 v[88:91], v[232:235], v[204:207], v[88:91]
	v_mfma_f32_16x16x32_bf16 v[84:87], v[240:243], v[204:207], v[84:87]
	v_mfma_f32_16x16x32_bf16 v[68:71], v[232:235], v[224:227], v[68:71]
	v_mfma_f32_16x16x32_bf16 v[64:67], v[240:243], v[224:227], v[64:67]
	v_mfma_f32_16x16x32_bf16 v[120:123], v[236:239], v[192:195], v[120:123]
	v_mfma_f32_16x16x32_bf16 v[116:119], v[244:247], v[192:195], v[116:119]
	v_mfma_f32_16x16x32_bf16 v[104:107], v[236:239], v[200:203], v[104:107]
	v_mfma_f32_16x16x32_bf16 v[100:103], v[244:247], v[200:203], v[100:103]
	v_mfma_f32_16x16x32_bf16 v[88:91], v[236:239], v[218:221], v[88:91]
	v_mfma_f32_16x16x32_bf16 v[84:87], v[244:247], v[218:221], v[84:87]
	v_mfma_f32_16x16x32_bf16 v[68:71], v[236:239], v[228:231], v[68:71]
	v_mfma_f32_16x16x32_bf16 v[64:67], v[244:247], v[228:231], v[64:67]
	s_setprio 0
	s_mov_b32 m0, s36
	v_lshl_add_u64 v[164:165], v[250:251], 0, s[88:89]
	s_barrier
	ds_read_b128 v[188:191], v159 offset:49152
	ds_read_b128 v[192:195], v159 offset:50176
	ds_read_b128 v[196:199], v159 offset:51200
	ds_read_b128 v[200:203], v159 offset:52224
	ds_read_b128 v[204:207], v159 offset:53248
	ds_read_b128 v[218:221], v159 offset:54272
	ds_read_b128 v[224:227], v159 offset:55296
	ds_read_b128 v[228:231], v159 offset:56320
	global_load_lds_dwordx4 v[164:165], off
	v_lshl_add_u64 v[164:165], v[210:211], 0, s[88:89]
	s_mov_b32 m0, s37
	s_nop 0
	global_load_lds_dwordx4 v[164:165], off
	v_cvt_pk_bf16_f32 v112, v112, v113
	v_cvt_pk_bf16_f32 v113, v114, v115
	v_cvt_pk_bf16_f32 v114, v108, v109
	v_cvt_pk_bf16_f32 v115, v110, v111
	s_add_u32 s78, s98, 0x2000
	s_addc_u32 s79, s99, 0
	global_store_dwordx4 v138, v[112:115], s[78:79] nt
	s_barrier
	s_waitcnt lgkmcnt(0)
	s_setprio 1
	s_waitcnt lgkmcnt(0)
	v_mfma_f32_16x16x32_bf16 v[60:63], v[160:163], v[188:191], v[60:63]
	v_mfma_f32_16x16x32_bf16 v[56:59], v[180:183], v[188:191], v[56:59]
	v_mfma_f32_16x16x32_bf16 v[44:47], v[160:163], v[196:199], v[44:47]
	v_mfma_f32_16x16x32_bf16 v[40:43], v[180:183], v[196:199], v[40:43]
	v_mfma_f32_16x16x32_bf16 v[28:31], v[160:163], v[204:207], v[28:31]
	v_mfma_f32_16x16x32_bf16 v[24:27], v[180:183], v[204:207], v[24:27]
	v_mfma_f32_16x16x32_bf16 v[12:15], v[160:163], v[224:227], v[12:15]
	v_mfma_f32_16x16x32_bf16 v[8:11], v[180:183], v[224:227], v[8:11]
	v_mfma_f32_16x16x32_bf16 v[60:63], v[176:179], v[192:195], v[60:63]
	v_mfma_f32_16x16x32_bf16 v[56:59], v[184:187], v[192:195], v[56:59]
	v_mfma_f32_16x16x32_bf16 v[44:47], v[176:179], v[200:203], v[44:47]
	v_mfma_f32_16x16x32_bf16 v[40:43], v[184:187], v[200:203], v[40:43]
	v_mfma_f32_16x16x32_bf16 v[28:31], v[176:179], v[218:221], v[28:31]
	v_mfma_f32_16x16x32_bf16 v[24:27], v[184:187], v[218:221], v[24:27]
	v_mfma_f32_16x16x32_bf16 v[12:15], v[176:179], v[228:231], v[12:15]
	v_mfma_f32_16x16x32_bf16 v[8:11], v[184:187], v[228:231], v[8:11]
	s_setprio 0
	s_barrier
	s_add_i32 s20, s20, s28
	v_lshl_add_u64 v[160:161], v[170:171], 0, s[88:89]
	s_mov_b32 m0, s20
	s_nop 0
	global_load_lds_dwordx4 v[160:161], off
	v_lshl_add_u64 v[160:161], v[172:173], 0, s[88:89]
	s_add_i32 m0, s20, 0x2000
	s_nop 0
	global_load_lds_dwordx4 v[160:161], off
	v_cvt_pk_bf16_f32 v96, v96, v97
	v_cvt_pk_bf16_f32 v97, v98, v99
	v_cvt_pk_bf16_f32 v98, v92, v93
	v_cvt_pk_bf16_f32 v99, v94, v95
	s_add_u32 s78, s98, 0x4000
	s_addc_u32 s79, s99, 0
	global_store_dwordx4 v138, v[96:99], s[78:79] nt
	s_waitcnt vmcnt(9)
	s_barrier
	s_setprio 1
	v_mfma_f32_16x16x32_bf16 v[52:55], v[232:235], v[188:191], v[52:55]
	v_mfma_f32_16x16x32_bf16 v[48:51], v[240:243], v[188:191], v[48:51]
	v_mfma_f32_16x16x32_bf16 v[36:39], v[232:235], v[196:199], v[36:39]
	v_mfma_f32_16x16x32_bf16 v[32:35], v[240:243], v[196:199], v[32:35]
	v_mfma_f32_16x16x32_bf16 v[20:23], v[232:235], v[204:207], v[20:23]
	v_mfma_f32_16x16x32_bf16 v[16:19], v[240:243], v[204:207], v[16:19]
	v_mfma_f32_16x16x32_bf16 v[4:7], v[232:235], v[224:227], v[4:7]
	v_mfma_f32_16x16x32_bf16 v[0:3], v[240:243], v[224:227], v[0:3]
	v_mfma_f32_16x16x32_bf16 v[52:55], v[236:239], v[192:195], v[52:55]
	v_mfma_f32_16x16x32_bf16 v[48:51], v[244:247], v[192:195], v[48:51]
	v_mfma_f32_16x16x32_bf16 v[36:39], v[236:239], v[200:203], v[36:39]
	v_mfma_f32_16x16x32_bf16 v[32:35], v[244:247], v[200:203], v[32:35]
	v_mfma_f32_16x16x32_bf16 v[20:23], v[236:239], v[218:221], v[20:23]
	v_mfma_f32_16x16x32_bf16 v[16:19], v[244:247], v[218:221], v[16:19]
	v_mfma_f32_16x16x32_bf16 v[4:7], v[236:239], v[228:231], v[4:7]
	v_mfma_f32_16x16x32_bf16 v[0:3], v[244:247], v[228:231], v[0:3]
	s_setprio 0
	s_add_u32 s44, s44, 0x100
	s_addc_u32 s45, s45, 0
	s_add_u32 s18, s18, 0x100
	s_addc_u32 s19, s19, 0
	s_mov_b32 s20, s46
	s_barrier
	s_and_b64 vcc, exec, s[6:7]
	s_cbranch_vccz .Lp2_next
	s_mov_b32 s47, 0x28000
	v_mov_b64_e32 v[246:247], v[174:175]
	v_mov_b64_e32 v[174:175], v[216:217]
	v_mov_b32_e32 v217, v209
	v_mov_b32_e32 v209, 0x7f800000
	s_branch .LBB0_214
.Lp2_next:
	v_cvt_pk_bf16_f32 v120, v120, v121
	v_cvt_pk_bf16_f32 v121, v122, v123
	v_cvt_pk_bf16_f32 v122, v116, v117
	v_cvt_pk_bf16_f32 v123, v118, v119
	v_cvt_pk_bf16_f32 v104, v104, v105
	v_cvt_pk_bf16_f32 v105, v106, v107
	v_cvt_pk_bf16_f32 v106, v100, v101
	v_cvt_pk_bf16_f32 v107, v102, v103
	v_cvt_pk_bf16_f32 v88, v88, v89
	v_cvt_pk_bf16_f32 v89, v90, v91
	v_cvt_pk_bf16_f32 v90, v84, v85
	v_cvt_pk_bf16_f32 v91, v86, v87
	v_cvt_pk_bf16_f32 v76, v76, v77
	v_cvt_pk_bf16_f32 v77, v78, v79
	v_cvt_pk_bf16_f32 v78, v72, v73
	v_cvt_pk_bf16_f32 v79, v74, v75
	v_cvt_pk_bf16_f32 v140, v68, v69
	v_cvt_pk_bf16_f32 v141, v70, v71
	v_cvt_pk_bf16_f32 v142, v64, v65
	v_cvt_pk_bf16_f32 v143, v66, v67
	v_cvt_pk_bf16_f32 v60, v60, v61
	v_cvt_pk_bf16_f32 v61, v62, v63
	v_cvt_pk_bf16_f32 v62, v56, v57
	v_cvt_pk_bf16_f32 v63, v58, v59
	v_cvt_pk_bf16_f32 v52, v52, v53
	v_cvt_pk_bf16_f32 v53, v54, v55
	v_cvt_pk_bf16_f32 v54, v48, v49
	v_cvt_pk_bf16_f32 v55, v50, v51
	v_cvt_pk_bf16_f32 v44, v44, v45
	v_cvt_pk_bf16_f32 v45, v46, v47
	v_cvt_pk_bf16_f32 v46, v40, v41
	v_cvt_pk_bf16_f32 v47, v42, v43
	v_cvt_pk_bf16_f32 v36, v36, v37
	v_cvt_pk_bf16_f32 v37, v38, v39
	v_cvt_pk_bf16_f32 v38, v32, v33
	v_cvt_pk_bf16_f32 v39, v34, v35
	v_cvt_pk_bf16_f32 v28, v28, v29
	v_cvt_pk_bf16_f32 v29, v30, v31
	v_cvt_pk_bf16_f32 v30, v24, v25
	v_cvt_pk_bf16_f32 v31, v26, v27
	v_cvt_pk_bf16_f32 v20, v20, v21
	v_cvt_pk_bf16_f32 v21, v22, v23
	v_cvt_pk_bf16_f32 v22, v16, v17
	v_cvt_pk_bf16_f32 v23, v18, v19
	v_cvt_pk_bf16_f32 v144, v12, v13
	v_cvt_pk_bf16_f32 v145, v14, v15
	v_cvt_pk_bf16_f32 v146, v8, v9
	v_cvt_pk_bf16_f32 v147, v10, v11
	v_cvt_pk_bf16_f32 v148, v4, v5
	v_cvt_pk_bf16_f32 v149, v6, v7
	v_cvt_pk_bf16_f32 v150, v0, v1
	v_cvt_pk_bf16_f32 v151, v2, v3
	s_mov_b32 s42, s40
	s_mov_b32 s43, s41
	s_mov_b64 s[20:21], s[8:9]
	s_mov_b64 s[18:19], s[10:11]
	s_add_u32 s22, s20, 0x80
	s_addc_u32 s23, s21, 0
	v_lshl_add_u64 v[164:165], s[22:23], 0, v[156:157]
	s_add_i32 m0, s29, 0xc000
	s_nop 0
	global_load_lds_dwordx4 v[164:165], off
	v_lshl_add_u64 v[164:165], s[22:23], 0, v[154:155]
	s_add_i32 m0, s29, 0xe000
	s_nop 0
	global_load_lds_dwordx4 v[164:165], off
	s_add_u32 s78, s98, 0x6000
	s_addc_u32 s79, s99, 0
	global_store_dwordx4 v138, v[76:79], s[78:79] nt
	s_add_u32 s78, s98, 0x0
	s_addc_u32 s79, s99, 0
	global_store_dwordx4 v138, v[120:123], s[78:79] offset:256 nt
	s_add_u32 s78, s98, 0x2000
	s_addc_u32 s79, s99, 0
	global_store_dwordx4 v138, v[104:107], s[78:79] offset:256 nt
	s_add_u32 s78, s98, 0x10000
	s_addc_u32 s79, s99, 0
	global_store_dwordx4 v138, v[60:63], s[78:79] nt
	s_add_u32 s78, s98, 0x12000
	s_addc_u32 s79, s99, 0
	global_store_dwordx4 v138, v[44:47], s[78:79] nt
	s_add_u32 s78, s98, 0x10000
	s_addc_u32 s79, s99, 0
	global_store_dwordx4 v138, v[52:55], s[78:79] offset:256 nt
	s_add_u32 s78, s98, 0x12000
	s_addc_u32 s79, s99, 0
	global_store_dwordx4 v138, v[36:39], s[78:79] offset:256 nt
	s_add_i32 s39, s39, 1
	s_mul_i32 s6, s3, s39
	s_mul_hi_u32 s7, s2, s39
	s_add_i32 s7, s7, s6
	s_mul_i32 s6, s2, s39
	s_add_u32 s10, s6, s64
	s_addc_u32 s11, s7, s65
	v_mov_b64_e32 v[160:161], 0xc40
	v_cmp_lt_i64_e64 s[8:9], s[10:11], v[160:161]
	v_mov_b64_e32 v[160:161], 0xc3f
	v_cmp_gt_i64_e64 s[6:7], s[10:11], v[160:161]
	s_and_b64 vcc, exec, s[6:7]
	s_cbranch_vccnz .Lp2_u217
	s_ashr_i32 s11, s10, 31
	s_lshr_b32 s11, s11, 29
	s_add_i32 s11, s10, s11
	s_ashr_i32 s22, s11, 3
	s_and_b32 s11, s11, -8
	s_sub_i32 s10, s10, s11
	s_cmp_lt_i32 s10, 0
	s_cselect_b32 s11, s69, 0x188
	s_mul_i32 s10, s10, s11
	s_add_i32 s10, s10, s22
	s_mul_hi_i32 s11, s10, 0x5397829d
	s_lshr_b32 s22, s11, 31
	s_ashr_i32 s11, s11, 6
	s_add_i32 s11, s11, s22
	s_lshl_b32 s22, s11, 2
	s_sub_i32 s23, 64, s22
	s_min_i32 s23, s23, 4
	s_abs_i32 s40, s23
	v_cvt_f32_u32_e32 v160, s40
	s_sub_i32 s44, 0, s40
	s_mulk_i32 s11, 0xc4
	s_sub_i32 s10, s10, s11
	v_rcp_iflag_f32_e32 v160, v160
	s_abs_i32 s11, s10
	s_xor_b32 s41, s10, s23
	s_ashr_i32 s41, s41, 31
	v_mul_f32_e32 v160, 0x4f7ffffe, v160
	v_cvt_u32_f32_e32 v160, v160
	s_nop 0
	v_readfirstlane_b32 s45, v160
	s_mul_i32 s44, s44, s45
	s_mul_hi_u32 s44, s45, s44
	s_add_i32 s45, s45, s44
	s_mul_hi_u32 s44, s11, s45
	s_mul_i32 s45, s44, s40
	s_sub_i32 s11, s11, s45
	s_add_i32 s46, s44, 1
	s_sub_i32 s45, s11, s40
	s_cmp_ge_u32 s11, s40
	s_cselect_b32 s44, s46, s44
	s_cselect_b32 s11, s45, s11
	s_add_i32 s45, s44, 1
	s_cmp_ge_u32 s11, s40
	s_cselect_b32 s11, s45, s44
	s_xor_b32 s11, s11, s41
	s_sub_i32 s40, s11, s41
	s_mul_i32 s11, s40, s23
	s_sub_i32 s10, s10, s11
	s_add_i32 s41, s22, s10

.Lp2_u221:
	s_add_u32 s44, s18, 0x100
	s_addc_u32 s45, s19, 0
	s_add_u32 s18, s20, 0x80
	s_addc_u32 s19, s21, 0
	s_mov_b32 s20, 0
	s_add_i32 s46, s20, 2
	s_add_u32 s22, s18, 0x80
	s_addc_u32 s21, s19, 0
	s_add_i32 s47, 0, 0x10000
	v_add_u32_e32 v164, s47, v158
	ds_read_b128 v[160:163], v164
	ds_read_b128 v[176:179], v164 offset:1024
	ds_read_b128 v[180:183], v164 offset:2048
	ds_read_b128 v[184:187], v164 offset:3072
	s_cmp_eq_u32 s38, s20
	s_cselect_b32 s20, s8, s22
	s_cselect_b32 s21, s9, s21
	s_cselect_b32 s23, s11, s45
	s_cselect_b32 s22, s10, s44
	ds_read_b128 v[188:191], v159
	ds_read_b128 v[192:195], v159 offset:1024
	ds_read_b128 v[196:199], v159 offset:2048
	ds_read_b128 v[200:203], v159 offset:3072
	ds_read_b128 v[204:207], v159 offset:4096
	ds_read_b128 v[218:221], v159 offset:5120
	ds_read_b128 v[224:227], v159 offset:6144
	ds_read_b128 v[228:231], v159 offset:7168
	s_add_u32 s78, s98, 0x4000
	s_addc_u32 s79, s99, 0
	global_store_dwordx4 v138, v[88:91], s[78:79] offset:256 nt
	s_waitcnt lgkmcnt(8)
	s_barrier
	s_waitcnt lgkmcnt(0)
	s_setprio 1
	s_waitcnt lgkmcnt(0)
	v_mfma_f32_16x16x32_bf16 v[124:127], v[160:163], v[188:191], 0
	v_mfma_f32_16x16x32_bf16 v[128:131], v[180:183], v[188:191], 0
	v_mfma_f32_16x16x32_bf16 v[112:115], v[160:163], v[196:199], 0
	v_mfma_f32_16x16x32_bf16 v[108:111], v[180:183], v[196:199], 0
	v_mfma_f32_16x16x32_bf16 v[96:99], v[160:163], v[204:207], 0
	v_mfma_f32_16x16x32_bf16 v[92:95], v[180:183], v[204:207], 0
	v_mfma_f32_16x16x32_bf16 v[76:79], v[160:163], v[224:227], 0
	v_mfma_f32_16x16x32_bf16 v[72:75], v[180:183], v[224:227], 0
	v_mfma_f32_16x16x32_bf16 v[124:127], v[176:179], v[192:195], v[124:127]
	v_mfma_f32_16x16x32_bf16 v[128:131], v[184:187], v[192:195], v[128:131]
	v_mfma_f32_16x16x32_bf16 v[112:115], v[176:179], v[200:203], v[112:115]
	v_mfma_f32_16x16x32_bf16 v[108:111], v[184:187], v[200:203], v[108:111]
	v_mfma_f32_16x16x32_bf16 v[96:99], v[176:179], v[218:221], v[96:99]
	v_mfma_f32_16x16x32_bf16 v[92:95], v[184:187], v[218:221], v[92:95]
	v_mfma_f32_16x16x32_bf16 v[76:79], v[176:179], v[228:231], v[76:79]
	v_mfma_f32_16x16x32_bf16 v[72:75], v[184:187], v[228:231], v[72:75]
	s_setprio 0
	s_barrier
	s_add_i32 s48, 0, 0x14000
	v_add_u32_e32 v164, s48, v158
	s_add_i32 s47, s47, s28
	ds_read_b128 v[232:235], v164
	ds_read_b128 v[236:239], v164 offset:1024
	ds_read_b128 v[240:243], v164 offset:2048
	ds_read_b128 v[244:247], v164 offset:3072
	v_lshl_add_u64 v[164:165], s[22:23], 0, v[166:167]
	s_mov_b32 m0, s47
	v_lshl_add_u64 v[248:249], s[22:23], 0, v[132:133]
	global_load_lds_dwordx4 v[164:165], off
	s_add_i32 m0, s47, 0x2000
	s_nop 0
	global_load_lds_dwordx4 v[248:249], off
	s_add_u32 s78, s98, 0x14000
	s_addc_u32 s79, s99, 0
	global_store_dwordx4 v138, v[28:31], s[78:79] nt
	s_barrier
	s_waitcnt lgkmcnt(0)
	s_setprio 1
	s_waitcnt lgkmcnt(0)
	v_mfma_f32_16x16x32_bf16 v[120:123], v[232:235], v[188:191], 0
	v_mfma_f32_16x16x32_bf16 v[116:119], v[240:243], v[188:191], 0
	v_mfma_f32_16x16x32_bf16 v[104:107], v[232:235], v[196:199], 0
	v_mfma_f32_16x16x32_bf16 v[100:103], v[240:243], v[196:199], 0
	v_mfma_f32_16x16x32_bf16 v[88:91], v[232:235], v[204:207], 0
	v_mfma_f32_16x16x32_bf16 v[84:87], v[240:243], v[204:207], 0
	v_mfma_f32_16x16x32_bf16 v[68:71], v[232:235], v[224:227], 0
	v_mfma_f32_16x16x32_bf16 v[64:67], v[240:243], v[224:227], 0
	v_mfma_f32_16x16x32_bf16 v[120:123], v[236:239], v[192:195], v[120:123]
	v_mfma_f32_16x16x32_bf16 v[116:119], v[244:247], v[192:195], v[116:119]
	v_mfma_f32_16x16x32_bf16 v[104:107], v[236:239], v[200:203], v[104:107]
	v_mfma_f32_16x16x32_bf16 v[100:103], v[244:247], v[200:203], v[100:103]
	v_mfma_f32_16x16x32_bf16 v[88:91], v[236:239], v[218:221], v[88:91]
	v_mfma_f32_16x16x32_bf16 v[84:87], v[244:247], v[218:221], v[84:87]
	v_mfma_f32_16x16x32_bf16 v[68:71], v[236:239], v[228:231], v[68:71]
	v_mfma_f32_16x16x32_bf16 v[64:67], v[244:247], v[228:231], v[64:67]
	s_setprio 0
	s_mov_b32 m0, s29
	v_lshl_add_u64 v[250:251], s[20:21], 0, v[136:137]
	s_barrier
	ds_read_b128 v[188:191], v159 offset:16384
	ds_read_b128 v[192:195], v159 offset:17408
	ds_read_b128 v[196:199], v159 offset:18432
	ds_read_b128 v[200:203], v159 offset:19456
	ds_read_b128 v[204:207], v159 offset:20480
	ds_read_b128 v[218:221], v159 offset:21504
	ds_read_b128 v[224:227], v159 offset:22528
	ds_read_b128 v[228:231], v159 offset:23552
	global_load_lds_dwordx4 v[250:251], off
	v_lshl_add_u64 v[210:211], s[20:21], 0, v[134:135]
	s_mov_b32 m0, s30
	s_nop 0
	global_load_lds_dwordx4 v[210:211], off
	s_add_u32 s78, s98, 0x14000
	s_addc_u32 s79, s99, 0
	global_store_dwordx4 v138, v[20:23], s[78:79] offset:256 nt
	s_barrier
	s_waitcnt lgkmcnt(0)
	s_setprio 1
	s_waitcnt lgkmcnt(0)
	v_mfma_f32_16x16x32_bf16 v[60:63], v[160:163], v[188:191], 0
	v_mfma_f32_16x16x32_bf16 v[56:59], v[180:183], v[188:191], 0
	v_mfma_f32_16x16x32_bf16 v[44:47], v[160:163], v[196:199], 0
	v_mfma_f32_16x16x32_bf16 v[40:43], v[180:183], v[196:199], 0
	v_mfma_f32_16x16x32_bf16 v[28:31], v[160:163], v[204:207], 0
	v_mfma_f32_16x16x32_bf16 v[24:27], v[180:183], v[204:207], 0
	v_mfma_f32_16x16x32_bf16 v[12:15], v[160:163], v[224:227], 0
	v_mfma_f32_16x16x32_bf16 v[8:11], v[180:183], v[224:227], 0
	v_mfma_f32_16x16x32_bf16 v[60:63], v[176:179], v[192:195], v[60:63]
	v_mfma_f32_16x16x32_bf16 v[56:59], v[184:187], v[192:195], v[56:59]
	v_mfma_f32_16x16x32_bf16 v[44:47], v[176:179], v[200:203], v[44:47]
	v_mfma_f32_16x16x32_bf16 v[40:43], v[184:187], v[200:203], v[40:43]
	v_mfma_f32_16x16x32_bf16 v[28:31], v[176:179], v[218:221], v[28:31]
	v_mfma_f32_16x16x32_bf16 v[24:27], v[184:187], v[218:221], v[24:27]
	v_mfma_f32_16x16x32_bf16 v[12:15], v[176:179], v[228:231], v[12:15]
	v_mfma_f32_16x16x32_bf16 v[8:11], v[184:187], v[228:231], v[8:11]
	s_setprio 0
	s_barrier
	s_add_u32 s22, s22, s12
	s_addc_u32 s23, s23, s13
	s_add_i32 s47, s48, s28
	v_lshl_add_u64 v[170:171], s[22:23], 0, v[166:167]
	s_mov_b32 m0, s47
	v_lshl_add_u64 v[172:173], s[22:23], 0, v[132:133]
	global_load_lds_dwordx4 v[170:171], off
	s_add_i32 m0, s47, 0x2000
	s_nop 0
	global_load_lds_dwordx4 v[172:173], off
	s_waitcnt vmcnt(16)
	s_barrier
	s_setprio 1
	v_mfma_f32_16x16x32_bf16 v[52:55], v[232:235], v[188:191], 0
	v_mfma_f32_16x16x32_bf16 v[48:51], v[240:243], v[188:191], 0
	v_mfma_f32_16x16x32_bf16 v[36:39], v[232:235], v[196:199], 0
	v_mfma_f32_16x16x32_bf16 v[32:35], v[240:243], v[196:199], 0
	v_mfma_f32_16x16x32_bf16 v[20:23], v[232:235], v[204:207], 0
	v_mfma_f32_16x16x32_bf16 v[16:19], v[240:243], v[204:207], 0
	v_mfma_f32_16x16x32_bf16 v[4:7], v[232:235], v[224:227], 0
	v_mfma_f32_16x16x32_bf16 v[0:3], v[240:243], v[224:227], 0
	v_mfma_f32_16x16x32_bf16 v[52:55], v[236:239], v[192:195], v[52:55]
	v_mfma_f32_16x16x32_bf16 v[48:51], v[244:247], v[192:195], v[48:51]
	v_mfma_f32_16x16x32_bf16 v[36:39], v[236:239], v[200:203], v[36:39]
	v_mfma_f32_16x16x32_bf16 v[32:35], v[244:247], v[200:203], v[32:35]
	v_mfma_f32_16x16x32_bf16 v[20:23], v[236:239], v[218:221], v[20:23]
	v_mfma_f32_16x16x32_bf16 v[16:19], v[244:247], v[218:221], v[16:19]
	v_mfma_f32_16x16x32_bf16 v[4:7], v[236:239], v[228:231], v[4:7]
	v_mfma_f32_16x16x32_bf16 v[0:3], v[244:247], v[228:231], v[0:3]
	s_setprio 0
	s_add_i32 s22, 0, 0x18000
	v_add_u32_e32 v169, s22, v158
	s_barrier
	ds_read_b128 v[160:163], v169
	ds_read_b128 v[176:179], v169 offset:1024
	ds_read_b128 v[180:183], v169 offset:2048
	ds_read_b128 v[184:187], v169 offset:3072
	s_add_u32 s20, s20, s12
	s_addc_u32 s21, s21, s13
	s_mov_b32 m0, s31
	v_lshl_add_u64 v[232:233], s[20:21], 0, v[136:137]
	ds_read_b128 v[188:191], v159 offset:32768
	ds_read_b128 v[192:195], v159 offset:33792
	ds_read_b128 v[196:199], v159 offset:34816
	ds_read_b128 v[200:203], v159 offset:35840
	ds_read_b128 v[204:207], v159 offset:36864
	ds_read_b128 v[218:221], v159 offset:37888
	ds_read_b128 v[224:227], v159 offset:38912
	ds_read_b128 v[228:231], v159 offset:39936
	global_load_lds_dwordx4 v[232:233], off
	v_lshl_add_u64 v[232:233], s[20:21], 0, v[134:135]
	s_mov_b32 m0, s34
	s_nop 0
	global_load_lds_dwordx4 v[232:233], off
	s_add_u32 s78, s98, 0x6000
	s_addc_u32 s79, s99, 0
	global_store_dwordx4 v138, v[140:143], s[78:79] offset:256 nt
	s_waitcnt lgkmcnt(8)
	s_barrier
	s_waitcnt lgkmcnt(0)
	s_setprio 1
	s_waitcnt lgkmcnt(0)
	v_mfma_f32_16x16x32_bf16 v[124:127], v[160:163], v[188:191], v[124:127]
	v_mfma_f32_16x16x32_bf16 v[128:131], v[180:183], v[188:191], v[128:131]
	v_mfma_f32_16x16x32_bf16 v[112:115], v[160:163], v[196:199], v[112:115]
	v_mfma_f32_16x16x32_bf16 v[108:111], v[180:183], v[196:199], v[108:111]
	v_mfma_f32_16x16x32_bf16 v[96:99], v[160:163], v[204:207], v[96:99]
	v_mfma_f32_16x16x32_bf16 v[92:95], v[180:183], v[204:207], v[92:95]
	v_mfma_f32_16x16x32_bf16 v[76:79], v[160:163], v[224:227], v[76:79]
	v_mfma_f32_16x16x32_bf16 v[72:75], v[180:183], v[224:227], v[72:75]
	v_mfma_f32_16x16x32_bf16 v[124:127], v[176:179], v[192:195], v[124:127]
	v_mfma_f32_16x16x32_bf16 v[128:131], v[184:187], v[192:195], v[128:131]
	v_mfma_f32_16x16x32_bf16 v[112:115], v[176:179], v[200:203], v[112:115]
	v_mfma_f32_16x16x32_bf16 v[108:111], v[184:187], v[200:203], v[108:111]
	v_mfma_f32_16x16x32_bf16 v[96:99], v[176:179], v[218:221], v[96:99]
	v_mfma_f32_16x16x32_bf16 v[92:95], v[184:187], v[218:221], v[92:95]
	v_mfma_f32_16x16x32_bf16 v[76:79], v[176:179], v[228:231], v[76:79]
	v_mfma_f32_16x16x32_bf16 v[72:75], v[184:187], v[228:231], v[72:75]
	s_setprio 0
	s_barrier
	s_add_i32 s20, 0, 0x1c000
	s_add_i32 s21, s22, s28
	v_add_u32_e32 v169, s20, v158
	v_lshl_add_u64 v[164:165], v[164:165], 0, s[88:89]
	s_mov_b32 m0, s21
	ds_read_b128 v[232:235], v169
	ds_read_b128 v[236:239], v169 offset:1024
	ds_read_b128 v[240:243], v169 offset:2048
	ds_read_b128 v[244:247], v169 offset:3072
	global_load_lds_dwordx4 v[164:165], off
	v_lshl_add_u64 v[164:165], v[248:249], 0, s[88:89]
	s_add_i32 m0, s21, 0x2000
	s_nop 0
	global_load_lds_dwordx4 v[164:165], off
	s_add_u32 s78, s98, 0x16000
	s_addc_u32 s79, s99, 0
	global_store_dwordx4 v138, v[144:147], s[78:79] nt
	s_barrier
	s_waitcnt lgkmcnt(0)
	s_setprio 1
	s_waitcnt lgkmcnt(0)
	v_mfma_f32_16x16x32_bf16 v[120:123], v[232:235], v[188:191], v[120:123]
	v_mfma_f32_16x16x32_bf16 v[116:119], v[240:243], v[188:191], v[116:119]
	v_mfma_f32_16x16x32_bf16 v[104:107], v[232:235], v[196:199], v[104:107]
	v_mfma_f32_16x16x32_bf16 v[100:103], v[240:243], v[196:199], v[100:103]
	v_mfma_f32_16x16x32_bf16 v[88:91], v[232:235], v[204:207], v[88:91]
	v_mfma_f32_16x16x32_bf16 v[84:87], v[240:243], v[204:207], v[84:87]
	v_mfma_f32_16x16x32_bf16 v[68:71], v[232:235], v[224:227], v[68:71]
	v_mfma_f32_16x16x32_bf16 v[64:67], v[240:243], v[224:227], v[64:67]
	v_mfma_f32_16x16x32_bf16 v[120:123], v[236:239], v[192:195], v[120:123]
	v_mfma_f32_16x16x32_bf16 v[116:119], v[244:247], v[192:195], v[116:119]
	v_mfma_f32_16x16x32_bf16 v[104:107], v[236:239], v[200:203], v[104:107]
	v_mfma_f32_16x16x32_bf16 v[100:103], v[244:247], v[200:203], v[100:103]
	v_mfma_f32_16x16x32_bf16 v[88:91], v[236:239], v[218:221], v[88:91]
	v_mfma_f32_16x16x32_bf16 v[84:87], v[244:247], v[218:221], v[84:87]
	v_mfma_f32_16x16x32_bf16 v[68:71], v[236:239], v[228:231], v[68:71]
	v_mfma_f32_16x16x32_bf16 v[64:67], v[244:247], v[228:231], v[64:67]
	s_setprio 0
	s_mov_b32 m0, s36
	v_lshl_add_u64 v[164:165], v[250:251], 0, s[88:89]
	s_barrier
	ds_read_b128 v[188:191], v159 offset:49152
	ds_read_b128 v[192:195], v159 offset:50176
	ds_read_b128 v[196:199], v159 offset:51200
	ds_read_b128 v[200:203], v159 offset:52224
	ds_read_b128 v[204:207], v159 offset:53248
	ds_read_b128 v[218:221], v159 offset:54272
	ds_read_b128 v[224:227], v159 offset:55296
	ds_read_b128 v[228:231], v159 offset:56320
	global_load_lds_dwordx4 v[164:165], off
	v_lshl_add_u64 v[164:165], v[210:211], 0, s[88:89]
	s_mov_b32 m0, s37
	s_nop 0
	global_load_lds_dwordx4 v[164:165], off
	s_add_u32 s78, s98, 0x16000
	s_addc_u32 s79, s99, 0
	global_store_dwordx4 v138, v[148:151], s[78:79] offset:256 nt
	s_barrier
	s_waitcnt lgkmcnt(0)
	s_setprio 1
	s_waitcnt lgkmcnt(0)
	v_mfma_f32_16x16x32_bf16 v[60:63], v[160:163], v[188:191], v[60:63]
	v_mfma_f32_16x16x32_bf16 v[56:59], v[180:183], v[188:191], v[56:59]
	v_mfma_f32_16x16x32_bf16 v[44:47], v[160:163], v[196:199], v[44:47]
	v_mfma_f32_16x16x32_bf16 v[40:43], v[180:183], v[196:199], v[40:43]
	v_mfma_f32_16x16x32_bf16 v[28:31], v[160:163], v[204:207], v[28:31]
	v_mfma_f32_16x16x32_bf16 v[24:27], v[180:183], v[204:207], v[24:27]
	v_mfma_f32_16x16x32_bf16 v[12:15], v[160:163], v[224:227], v[12:15]
	v_mfma_f32_16x16x32_bf16 v[8:11], v[180:183], v[224:227], v[8:11]
	v_mfma_f32_16x16x32_bf16 v[60:63], v[176:179], v[192:195], v[60:63]
	v_mfma_f32_16x16x32_bf16 v[56:59], v[184:187], v[192:195], v[56:59]
	v_mfma_f32_16x16x32_bf16 v[44:47], v[176:179], v[200:203], v[44:47]
	v_mfma_f32_16x16x32_bf16 v[40:43], v[184:187], v[200:203], v[40:43]
	v_mfma_f32_16x16x32_bf16 v[28:31], v[176:179], v[218:221], v[28:31]
	v_mfma_f32_16x16x32_bf16 v[24:27], v[184:187], v[218:221], v[24:27]
	v_mfma_f32_16x16x32_bf16 v[12:15], v[176:179], v[228:231], v[12:15]
	v_mfma_f32_16x16x32_bf16 v[8:11], v[184:187], v[228:231], v[8:11]
	s_setprio 0
	s_barrier
	s_add_i32 s20, s20, s28
	v_lshl_add_u64 v[160:161], v[170:171], 0, s[88:89]
	s_mov_b32 m0, s20
	s_nop 0
	global_load_lds_dwordx4 v[160:161], off
	v_lshl_add_u64 v[160:161], v[172:173], 0, s[88:89]
	s_add_i32 m0, s20, 0x2000
	s_nop 0
	global_load_lds_dwordx4 v[160:161], off
	s_waitcnt vmcnt(9)
	s_barrier
	s_setprio 1
	v_mfma_f32_16x16x32_bf16 v[52:55], v[232:235], v[188:191], v[52:55]
	v_mfma_f32_16x16x32_bf16 v[48:51], v[240:243], v[188:191], v[48:51]
	v_mfma_f32_16x16x32_bf16 v[36:39], v[232:235], v[196:199], v[36:39]
	v_mfma_f32_16x16x32_bf16 v[32:35], v[240:243], v[196:199], v[32:35]
	v_mfma_f32_16x16x32_bf16 v[20:23], v[232:235], v[204:207], v[20:23]
	v_mfma_f32_16x16x32_bf16 v[16:19], v[240:243], v[204:207], v[16:19]
	v_mfma_f32_16x16x32_bf16 v[4:7], v[232:235], v[224:227], v[4:7]
	v_mfma_f32_16x16x32_bf16 v[0:3], v[240:243], v[224:227], v[0:3]
	v_mfma_f32_16x16x32_bf16 v[52:55], v[236:239], v[192:195], v[52:55]
	v_mfma_f32_16x16x32_bf16 v[48:51], v[244:247], v[192:195], v[48:51]
	v_mfma_f32_16x16x32_bf16 v[36:39], v[236:239], v[200:203], v[36:39]
	v_mfma_f32_16x16x32_bf16 v[32:35], v[244:247], v[200:203], v[32:35]
	v_mfma_f32_16x16x32_bf16 v[20:23], v[236:239], v[218:221], v[20:23]
	v_mfma_f32_16x16x32_bf16 v[16:19], v[244:247], v[218:221], v[16:19]
	v_mfma_f32_16x16x32_bf16 v[4:7], v[236:239], v[228:231], v[4:7]
	v_mfma_f32_16x16x32_bf16 v[0:3], v[244:247], v[228:231], v[0:3]
	s_setprio 0
	s_add_u32 s44, s44, 0x100
	s_addc_u32 s45, s45, 0
	s_add_u32 s18, s18, 0x100
	s_addc_u32 s19, s19, 0
	s_mov_b32 s20, s46
	s_barrier
	s_branch .LBB0_223

.LBB0_287:
	s_mov_b64 s[6:7], s[62:63]
	v_mov_b32_e32 v0, 0
	global_load_dwordx2 v[6:7], v0, s[6:7] offset:192
	global_load_dwordx2 v[12:13], v0, s[6:7] offset:16
	global_load_dwordx2 v[10:11], v0, s[6:7] offset:120
	s_bfe_u32 s76, s86, 0x40001
	v_mov_b32_e32 v8, v208
	s_and_b32 s5, s86, 1
	s_lshl_b32 s10, s76, 7
	s_lshl_b32 s9, s5, 6
	s_add_i32 s8, s10, 0xffffff80
	v_and_b32_e32 v9, 7, v8
	v_ashrrev_i32_e32 v1, 3, v8
	s_lshl_b32 s6, s86, 6
	v_lshl_or_b32 v5, v9, 3, s9
	v_add_u32_e32 v15, s8, v1
	s_mov_b64 s[2:3], 0x74c2800
	v_mov_b32_e32 v2, 0
	v_mov_b32_e32 v3, 0
	v_mov_b32_e32 v4, 0
	s_and_b32 s11, s6, 0xfffff800
	v_cmp_lt_i32_e32 vcc, -1, v15
	v_lshlrev_b32_e32 v14, 1, v5
	v_mov_b32_e32 v5, 0
	s_waitcnt vmcnt(2)
	v_lshl_add_u64 v[112:113], v[6:7], 0, s[2:3]
	s_mov_b32 s0, 0x200000
	s_mov_b64 s[2:3], 0x200000
	v_lshl_add_u32 v16, v9, 4, 0
	v_mov_b32_e32 v15, v167
	v_mov_b32_e32 v49, 0
	v_add_u32_e32 v44, 0, v1
	v_mad_u32_u24 v140, v44, s94, v16
	v_add_u32_e32 v45, s8, v44
	v_cmp_lt_i32_e32 vcc, -1, v45
	v_mov_b32_e32 v116, 0
	v_mov_b32_e32 v117, 0
	v_mov_b32_e32 v118, 0
	v_mov_b32_e32 v119, 0
	s_and_saveexec_b64 s[6:7], vcc
	s_cbranch_execz .Lswa_k0
	v_add_u32_e32 v46, s11, v45
	v_lshrrev_b32_e32 v47, 8, v46
	v_mad_u64_u32 v[132:133], s[12:13], v47, s77, v[112:113]
	v_lshlrev_b32_e32 v48, 9, v46
	v_and_b32_e32 v48, 0x1fe00, v48
	v_lshl_add_u64 v[132:133], v[132:133], 0, v[48:49]
	v_lshl_add_u64 v[132:133], v[132:133], 0, v[14:15]
	v_lshl_add_u64 v[132:133], v[132:133], 0, s[2:3]
	global_load_dwordx4 v[116:119], v[132:133], off
.Lswa_k0:
	s_or_b64 exec, exec, s[6:7]
	v_add_u32_e32 v44, 64, v1
	v_mad_u32_u24 v141, v44, s94, v16
	v_add_u32_e32 v45, s8, v44
	v_cmp_lt_i32_e32 vcc, -1, v45
	v_mov_b32_e32 v120, 0
	v_mov_b32_e32 v121, 0
	v_mov_b32_e32 v122, 0
	v_mov_b32_e32 v123, 0
	s_and_saveexec_b64 s[6:7], vcc
	s_cbranch_execz .Lswa_k1
	v_add_u32_e32 v46, s11, v45
	v_lshrrev_b32_e32 v47, 8, v46
	v_mad_u64_u32 v[132:133], s[12:13], v47, s77, v[112:113]
	v_lshlrev_b32_e32 v48, 9, v46
	v_and_b32_e32 v48, 0x1fe00, v48
	v_lshl_add_u64 v[132:133], v[132:133], 0, v[48:49]
	v_lshl_add_u64 v[132:133], v[132:133], 0, v[14:15]
	v_lshl_add_u64 v[132:133], v[132:133], 0, s[2:3]
	global_load_dwordx4 v[120:123], v[132:133], off
.Lswa_k1:
	s_or_b64 exec, exec, s[6:7]
	v_add_u32_e32 v44, 128, v1
	v_mad_u32_u24 v142, v44, s94, v16
	v_add_u32_e32 v45, s8, v44
	v_cmp_lt_i32_e32 vcc, -1, v45
	v_mov_b32_e32 v124, 0
	v_mov_b32_e32 v125, 0
	v_mov_b32_e32 v126, 0
	v_mov_b32_e32 v127, 0
	s_and_saveexec_b64 s[6:7], vcc
	s_cbranch_execz .Lswa_k2
	v_add_u32_e32 v46, s11, v45
	v_lshrrev_b32_e32 v47, 8, v46
	v_mad_u64_u32 v[132:133], s[12:13], v47, s77, v[112:113]
	v_lshlrev_b32_e32 v48, 9, v46
	v_and_b32_e32 v48, 0x1fe00, v48
	v_lshl_add_u64 v[132:133], v[132:133], 0, v[48:49]
	v_lshl_add_u64 v[132:133], v[132:133], 0, v[14:15]
	v_lshl_add_u64 v[132:133], v[132:133], 0, s[2:3]
	global_load_dwordx4 v[124:127], v[132:133], off
.Lswa_k2:
	s_or_b64 exec, exec, s[6:7]
	v_add_u32_e32 v44, 192, v1
	v_mad_u32_u24 v143, v44, s94, v16
	v_add_u32_e32 v45, s8, v44
	v_cmp_lt_i32_e32 vcc, -1, v45
	v_mov_b32_e32 v128, 0
	v_mov_b32_e32 v129, 0
	v_mov_b32_e32 v130, 0
	v_mov_b32_e32 v131, 0
	s_and_saveexec_b64 s[6:7], vcc
	s_cbranch_execz .Lswa_k3
	v_add_u32_e32 v46, s11, v45
	v_lshrrev_b32_e32 v47, 8, v46
	v_mad_u64_u32 v[132:133], s[12:13], v47, s77, v[112:113]
	v_lshlrev_b32_e32 v48, 9, v46
	v_and_b32_e32 v48, 0x1fe00, v48
	v_lshl_add_u64 v[132:133], v[132:133], 0, v[48:49]
	v_lshl_add_u64 v[132:133], v[132:133], 0, v[14:15]
	v_lshl_add_u64 v[132:133], v[132:133], 0, s[2:3]
	global_load_dwordx4 v[128:131], v[132:133], off
.Lswa_k3:
	s_or_b64 exec, exec, s[6:7]
	v_add_u32_e32 v9, 0x200, v8
	v_add_u32_e32 v17, 0x400, v8
	v_add_u32_e32 v5, 0x600, v8
	v_ashrrev_i32_e32 v1, 5, v9
	v_add_u32_e32 v2, s8, v1
	v_max_i32_e32 v2, 0, v2
	v_add_u32_e32 v9, s11, v2
	v_ashrrev_i32_e32 v14, 31, v9
	v_alignbit_b32 v2, v14, v9, 8
	v_lshlrev_b32_e32 v0, 1, v8
	v_mad_u64_u32 v[2:3], s[6:7], v2, s77, v[112:113]
	v_lshlrev_b32_e32 v9, 9, v9
	v_and_or_b32 v4, v0, 62, s9
	v_mad_u32_u24 v3, v14, s77, v3
	v_and_b32_e32 v166, 0x1fe00, v9
	v_lshl_add_u64 v[2:3], v[2:3], 0, v[166:167]
	v_lshlrev_b32_e32 v166, 1, v4
	v_lshl_add_u64 v[2:3], v[2:3], 0, v[166:167]
	v_add_co_u32_e32 v2, vcc, s0, v2
	v_ashrrev_i32_e32 v5, 5, v5
	s_nop 0
	v_addc_co_u32_e32 v3, vcc, 0, v3, vcc
	global_load_dword v2, v[2:3], off offset:256
	v_ashrrev_i32_e32 v3, 5, v17
	v_add_u32_e32 v4, s8, v3
	v_max_i32_e32 v4, 0, v4
	v_add_u32_e32 v4, s11, v4
	v_ashrrev_i32_e32 v9, 31, v4
	v_alignbit_b32 v14, v9, v4, 8
	v_mad_u64_u32 v[14:15], s[6:7], v14, s77, v[112:113]
	v_lshlrev_b32_e32 v4, 9, v4
	v_mad_u32_u24 v15, v9, s77, v15
	v_and_b32_e32 v16, 0x1fe00, v4
	v_mov_b32_e32 v17, v167
	v_lshl_add_u64 v[14:15], v[14:15], 0, v[16:17]
	v_add_u32_e32 v9, s8, v5
	v_lshl_add_u64 v[14:15], v[14:15], 0, v[166:167]
	v_max_i32_e32 v9, 0, v9
	v_add_co_u32_e32 v14, vcc, s0, v14
	v_add_u32_e32 v9, s11, v9
	s_nop 0
	v_addc_co_u32_e32 v15, vcc, 0, v15, vcc
	v_ashrrev_i32_e32 v16, 31, v9
	global_load_dword v4, v[14:15], off offset:256
	v_alignbit_b32 v14, v16, v9, 8
	v_mad_u64_u32 v[14:15], s[6:7], v14, s77, v[112:113]
	v_lshlrev_b32_e32 v9, 9, v9
	v_mad_u32_u24 v15, v16, s77, v15
	v_and_b32_e32 v16, 0x1fe00, v9
	v_lshl_add_u64 v[14:15], v[14:15], 0, v[16:17]
	v_lshl_add_u64 v[14:15], v[14:15], 0, v[166:167]
	v_add_co_u32_e32 v14, vcc, s0, v14
	v_mov_b32_e32 v19, v167
	s_nop 0
	v_addc_co_u32_e32 v15, vcc, 0, v15, vcc
	global_load_dword v9, v[14:15], off offset:256
	v_add_u32_e32 v14, 0x800, v8
	v_ashrrev_i32_e32 v14, 5, v14
	v_add_u32_e32 v15, s8, v14
	v_max_i32_e32 v15, 0, v15
	v_add_u32_e32 v15, s11, v15
	v_ashrrev_i32_e32 v18, 31, v15
	v_alignbit_b32 v16, v18, v15, 8
	v_mad_u64_u32 v[16:17], s[6:7], v16, s77, v[112:113]
	v_lshlrev_b32_e32 v15, 9, v15
	v_mad_u32_u24 v17, v18, s77, v17
	v_and_b32_e32 v18, 0x1fe00, v15
	v_lshl_add_u64 v[16:17], v[16:17], 0, v[18:19]
	v_lshl_add_u64 v[16:17], v[16:17], 0, v[166:167]
	v_add_co_u32_e32 v16, vcc, s0, v16
	v_mov_b32_e32 v21, v167
	s_nop 0
	v_addc_co_u32_e32 v17, vcc, 0, v17, vcc
	global_load_dword v15, v[16:17], off offset:256
	v_add_u32_e32 v16, 0xa00, v8
	v_ashrrev_i32_e32 v16, 5, v16
	v_add_u32_e32 v17, s8, v16
	v_max_i32_e32 v17, 0, v17
	v_add_u32_e32 v17, s11, v17
	v_ashrrev_i32_e32 v20, 31, v17
	v_alignbit_b32 v18, v20, v17, 8
	v_mad_u64_u32 v[18:19], s[6:7], v18, s77, v[112:113]
	v_lshlrev_b32_e32 v17, 9, v17
	v_mad_u32_u24 v19, v20, s77, v19
	v_and_b32_e32 v20, 0x1fe00, v17
	v_lshl_add_u64 v[18:19], v[18:19], 0, v[20:21]
	v_lshl_add_u64 v[18:19], v[18:19], 0, v[166:167]
	v_add_co_u32_e32 v18, vcc, s0, v18
	v_mov_b32_e32 v23, v167
	s_nop 0
	v_addc_co_u32_e32 v19, vcc, 0, v19, vcc
	global_load_dword v17, v[18:19], off offset:256
	v_add_u32_e32 v18, 0xc00, v8
	v_ashrrev_i32_e32 v18, 5, v18
	v_add_u32_e32 v19, s8, v18
	v_max_i32_e32 v19, 0, v19
	v_add_u32_e32 v19, s11, v19
	v_ashrrev_i32_e32 v22, 31, v19
	v_alignbit_b32 v20, v22, v19, 8
	v_mad_u64_u32 v[20:21], s[6:7], v20, s77, v[112:113]
	v_lshlrev_b32_e32 v19, 9, v19
	v_mad_u32_u24 v21, v22, s77, v21
	v_and_b32_e32 v22, 0x1fe00, v19
	v_lshl_add_u64 v[20:21], v[20:21], 0, v[22:23]
	v_lshl_add_u64 v[20:21], v[20:21], 0, v[166:167]
	v_add_co_u32_e32 v20, vcc, s0, v20
	v_mov_b32_e32 v25, v167
	s_nop 0
	v_addc_co_u32_e32 v21, vcc, 0, v21, vcc
	global_load_dword v19, v[20:21], off offset:256
	v_add_u32_e32 v20, 0xe00, v8
	v_ashrrev_i32_e32 v20, 5, v20
	v_add_u32_e32 v21, s8, v20
	v_max_i32_e32 v21, 0, v21
	v_add_u32_e32 v21, s11, v21
	v_ashrrev_i32_e32 v24, 31, v21
	v_alignbit_b32 v22, v24, v21, 8
	v_mad_u64_u32 v[22:23], s[6:7], v22, s77, v[112:113]
	v_lshlrev_b32_e32 v21, 9, v21
	v_mad_u32_u24 v23, v24, s77, v23
	v_and_b32_e32 v24, 0x1fe00, v21
	v_lshl_add_u64 v[22:23], v[22:23], 0, v[24:25]
	v_lshl_add_u64 v[22:23], v[22:23], 0, v[166:167]
	v_add_co_u32_e32 v22, vcc, s0, v22
	v_mov_b32_e32 v27, v167
	s_nop 0
	v_addc_co_u32_e32 v23, vcc, 0, v23, vcc
	global_load_dword v21, v[22:23], off offset:256
	v_add_u32_e32 v22, 0x1000, v8
	v_ashrrev_i32_e32 v22, 5, v22
	v_add_u32_e32 v23, s8, v22
	v_max_i32_e32 v23, 0, v23
	v_add_u32_e32 v23, s11, v23
	v_ashrrev_i32_e32 v26, 31, v23
	v_alignbit_b32 v24, v26, v23, 8
	v_mad_u64_u32 v[24:25], s[6:7], v24, s77, v[112:113]
	v_lshlrev_b32_e32 v23, 9, v23
	v_mad_u32_u24 v25, v26, s77, v25
	v_and_b32_e32 v26, 0x1fe00, v23
	v_lshl_add_u64 v[24:25], v[24:25], 0, v[26:27]
	v_lshl_add_u64 v[24:25], v[24:25], 0, v[166:167]
	v_add_co_u32_e32 v24, vcc, s0, v24
	v_add_u32_e32 v23, 0x1200, v8
	s_nop 0
	v_addc_co_u32_e32 v25, vcc, 0, v25, vcc
	v_ashrrev_i32_e32 v23, 5, v23
	global_load_dword v24, v[24:25], off offset:256
	v_add_u32_e32 v25, s8, v23
	v_max_i32_e32 v25, 0, v25
	v_add_u32_e32 v25, s11, v25
	v_ashrrev_i32_e32 v28, 31, v25
	v_alignbit_b32 v26, v28, v25, 8
	v_mad_u64_u32 v[26:27], s[6:7], v26, s77, v[112:113]
	v_lshlrev_b32_e32 v25, 9, v25
	v_mad_u32_u24 v27, v28, s77, v27
	v_and_b32_e32 v28, 0x1fe00, v25
	v_mov_b32_e32 v29, v167
	v_lshl_add_u64 v[26:27], v[26:27], 0, v[28:29]
	v_lshl_add_u64 v[26:27], v[26:27], 0, v[166:167]
	v_add_co_u32_e32 v26, vcc, s0, v26
	v_mov_b32_e32 v31, v167
	s_nop 0
	v_addc_co_u32_e32 v27, vcc, 0, v27, vcc
	global_load_dword v25, v[26:27], off offset:256
	v_add_u32_e32 v26, 0x1400, v8
	v_ashrrev_i32_e32 v26, 5, v26
	v_add_u32_e32 v27, s8, v26
	v_max_i32_e32 v27, 0, v27
	v_add_u32_e32 v27, s11, v27
	v_ashrrev_i32_e32 v30, 31, v27
	v_alignbit_b32 v28, v30, v27, 8
	v_mad_u64_u32 v[28:29], s[6:7], v28, s77, v[112:113]
	v_lshlrev_b32_e32 v27, 9, v27
	v_mad_u32_u24 v29, v30, s77, v29
	v_and_b32_e32 v30, 0x1fe00, v27
	v_lshl_add_u64 v[28:29], v[28:29], 0, v[30:31]
	v_lshl_add_u64 v[28:29], v[28:29], 0, v[166:167]
	v_add_co_u32_e32 v28, vcc, s0, v28
	v_mov_b32_e32 v33, v167
	s_nop 0
	v_addc_co_u32_e32 v29, vcc, 0, v29, vcc
	global_load_dword v27, v[28:29], off offset:256
	v_add_u32_e32 v28, 0x1600, v8
	v_ashrrev_i32_e32 v28, 5, v28
	v_add_u32_e32 v29, s8, v28
	v_max_i32_e32 v29, 0, v29
	v_add_u32_e32 v29, s11, v29
	v_ashrrev_i32_e32 v32, 31, v29
	v_alignbit_b32 v30, v32, v29, 8
	v_mad_u64_u32 v[30:31], s[6:7], v30, s77, v[112:113]
	v_lshlrev_b32_e32 v29, 9, v29
	v_mad_u32_u24 v31, v32, s77, v31
	v_and_b32_e32 v32, 0x1fe00, v29
	v_lshl_add_u64 v[30:31], v[30:31], 0, v[32:33]
	v_lshl_add_u64 v[30:31], v[30:31], 0, v[166:167]
	v_add_co_u32_e32 v30, vcc, s0, v30
	v_mov_b32_e32 v35, v167
	s_nop 0
	v_addc_co_u32_e32 v31, vcc, 0, v31, vcc
	global_load_dword v29, v[30:31], off offset:256
	v_add_u32_e32 v30, 0x1800, v8
	v_ashrrev_i32_e32 v30, 5, v30
	v_add_u32_e32 v31, s8, v30
	v_max_i32_e32 v31, 0, v31
	v_add_u32_e32 v31, s11, v31
	v_ashrrev_i32_e32 v34, 31, v31
	v_alignbit_b32 v32, v34, v31, 8
	v_mad_u64_u32 v[32:33], s[6:7], v32, s77, v[112:113]
	v_lshlrev_b32_e32 v31, 9, v31
	v_mad_u32_u24 v33, v34, s77, v33
	v_and_b32_e32 v34, 0x1fe00, v31
	v_lshl_add_u64 v[32:33], v[32:33], 0, v[34:35]
	v_lshl_add_u64 v[32:33], v[32:33], 0, v[166:167]
	v_add_co_u32_e32 v32, vcc, s0, v32
	v_mov_b32_e32 v37, v167
	s_nop 0
	v_addc_co_u32_e32 v33, vcc, 0, v33, vcc
	global_load_dword v31, v[32:33], off offset:256
	v_add_u32_e32 v32, 0x1a00, v8
	v_ashrrev_i32_e32 v32, 5, v32
	v_add_u32_e32 v33, s8, v32
	v_max_i32_e32 v33, 0, v33
	v_add_u32_e32 v33, s11, v33
	v_ashrrev_i32_e32 v36, 31, v33
	v_alignbit_b32 v34, v36, v33, 8
	v_mad_u64_u32 v[34:35], s[6:7], v34, s77, v[112:113]
	v_lshlrev_b32_e32 v33, 9, v33
	v_mad_u32_u24 v35, v36, s77, v35
	v_and_b32_e32 v36, 0x1fe00, v33
	v_lshl_add_u64 v[34:35], v[34:35], 0, v[36:37]
	v_lshl_add_u64 v[34:35], v[34:35], 0, v[166:167]
	v_add_co_u32_e32 v34, vcc, s0, v34
	v_mov_b32_e32 v39, v167
	s_nop 0
	v_addc_co_u32_e32 v35, vcc, 0, v35, vcc
	global_load_dword v33, v[34:35], off offset:256
	v_add_u32_e32 v34, 0x1c00, v8
	v_ashrrev_i32_e32 v34, 5, v34
	v_add_u32_e32 v35, s8, v34
	v_max_i32_e32 v35, 0, v35
	v_add_u32_e32 v35, s11, v35
	v_ashrrev_i32_e32 v38, 31, v35
	v_alignbit_b32 v36, v38, v35, 8
	v_mad_u64_u32 v[36:37], s[6:7], v36, s77, v[112:113]
	v_lshlrev_b32_e32 v35, 9, v35
	v_mad_u32_u24 v37, v38, s77, v37
	v_and_b32_e32 v38, 0x1fe00, v35
	v_lshl_add_u64 v[36:37], v[36:37], 0, v[38:39]
	v_lshl_add_u64 v[36:37], v[36:37], 0, v[166:167]
	v_add_co_u32_e32 v36, vcc, s0, v36
	v_mov_b32_e32 v41, v167
	s_nop 0
	v_addc_co_u32_e32 v37, vcc, 0, v37, vcc
	global_load_dword v35, v[36:37], off offset:256
	v_add_u32_e32 v36, 0x1e00, v8
	v_ashrrev_i32_e32 v36, 5, v36
	v_add_u32_e32 v37, s8, v36
	v_max_i32_e32 v37, 0, v37
	v_add_u32_e32 v37, s11, v37
	v_ashrrev_i32_e32 v40, 31, v37
	v_alignbit_b32 v38, v40, v37, 8
	v_mad_u64_u32 v[38:39], s[6:7], v38, s77, v[112:113]
	v_lshlrev_b32_e32 v37, 9, v37
	v_mad_u32_u24 v39, v40, s77, v39
	v_and_b32_e32 v40, 0x1fe00, v37
	v_lshl_add_u64 v[38:39], v[38:39], 0, v[40:41]
	v_lshl_add_u64 v[38:39], v[38:39], 0, v[166:167]
	v_add_co_u32_e32 v38, vcc, 0x200000, v38
	v_ashrrev_i32_e32 v0, 5, v8
	s_nop 0
	v_addc_co_u32_e32 v39, vcc, 0, v39, vcc
	global_load_dword v37, v[38:39], off offset:256
	s_sub_i32 s9, 0x7f, s10
	v_cmp_lt_i32_e32 vcc, s9, v0
	v_mov_b32_e32 v38, 0
	s_and_saveexec_b64 s[6:7], vcc
	s_cbranch_execz .LBB0_297
	s_add_i32 s12, s11, s8
	v_add_u32_e32 v40, s12, v0
	v_ashrrev_i32_e32 v41, 31, v40
	v_alignbit_b32 v38, v41, v40, 8
	v_mad_u64_u32 v[38:39], s[12:13], v38, s77, v[112:113]
	v_lshlrev_b32_e32 v40, 9, v40
	v_mad_u32_u24 v39, v41, s77, v39
	v_and_b32_e32 v40, 0x1fe00, v40
	v_mov_b32_e32 v41, v167
	v_lshl_add_u64 v[38:39], v[38:39], 0, v[40:41]
	v_lshl_add_u64 v[38:39], v[38:39], 0, v[166:167]
	v_add_co_u32_e32 v38, vcc, 0x200000, v38
	s_nop 1
	v_addc_co_u32_e32 v39, vcc, 0, v39, vcc
	global_load_dword v38, v[38:39], off offset:256
.LBB0_297:
	s_or_b64 exec, exec, s[6:7]
	v_and_b32_e32 v145, 31, v8
	v_lshl_add_u32 v40, v145, 2, s92
	v_cmp_lt_i32_e32 vcc, s9, v1
	v_mad_u64_u32 v[42:43], s[6:7], v0, s93, v[40:41]
	s_waitcnt vmcnt(14)
	v_cndmask_b32_e32 v2, 0, v2, vcc
	v_mad_u64_u32 v[0:1], s[6:7], v1, s93, v[40:41]
	v_cmp_lt_i32_e32 vcc, s9, v3
	s_waitcnt vmcnt(0)
	ds_write_b128 v140, v[116:119]
	ds_write_b128 v141, v[120:123]
	ds_write_b128 v142, v[124:127]
	ds_write_b128 v143, v[128:131]
	ds_write_b32 v42, v38
	ds_write_b32 v0, v2
	v_cndmask_b32_e32 v2, 0, v4, vcc
	v_mad_u64_u32 v[0:1], s[6:7], v3, s93, v[40:41]
	v_cmp_lt_i32_e32 vcc, s9, v5
	ds_write_b32 v0, v2
	v_mad_u64_u32 v[0:1], s[6:7], v5, s93, v[40:41]
	v_cndmask_b32_e32 v2, 0, v9, vcc
	v_cmp_lt_i32_e32 vcc, s9, v14
	ds_write_b32 v0, v2
	v_mad_u64_u32 v[0:1], s[6:7], v14, s93, v[40:41]
	v_cndmask_b32_e32 v2, 0, v15, vcc
	v_cmp_lt_i32_e32 vcc, s9, v16
	ds_write_b32 v0, v2
	v_mad_u64_u32 v[0:1], s[6:7], v16, s93, v[40:41]
	v_cndmask_b32_e32 v2, 0, v17, vcc
	v_cmp_lt_i32_e32 vcc, s9, v18
	ds_write_b32 v0, v2
	v_mad_u64_u32 v[0:1], s[6:7], v18, s93, v[40:41]
	v_cndmask_b32_e32 v2, 0, v19, vcc
	v_cmp_lt_i32_e32 vcc, s9, v20
	ds_write_b32 v0, v2
	v_mad_u64_u32 v[0:1], s[6:7], v20, s93, v[40:41]
	v_cndmask_b32_e32 v2, 0, v21, vcc
	v_cmp_lt_i32_e32 vcc, s9, v22
	ds_write_b32 v0, v2
	v_mad_u64_u32 v[0:1], s[6:7], v22, s93, v[40:41]
	v_cndmask_b32_e32 v2, 0, v24, vcc
	v_cmp_lt_i32_e32 vcc, s9, v23
	ds_write_b32 v0, v2
	v_mad_u64_u32 v[0:1], s[6:7], v23, s93, v[40:41]
	v_cndmask_b32_e32 v2, 0, v25, vcc
	v_cmp_lt_i32_e32 vcc, s9, v26
	ds_write_b32 v0, v2
	v_mad_u64_u32 v[0:1], s[6:7], v26, s93, v[40:41]
	v_cndmask_b32_e32 v2, 0, v27, vcc
	v_cmp_lt_i32_e32 vcc, s9, v28
	ds_write_b32 v0, v2
	v_mad_u64_u32 v[0:1], s[6:7], v28, s93, v[40:41]
	v_cndmask_b32_e32 v2, 0, v29, vcc
	v_cmp_lt_i32_e32 vcc, s9, v30
	ds_write_b32 v0, v2
	v_mad_u64_u32 v[0:1], s[6:7], v30, s93, v[40:41]
	v_cndmask_b32_e32 v2, 0, v31, vcc
	v_cmp_lt_i32_e32 vcc, s9, v32
	ds_write_b32 v0, v2
	v_mad_u64_u32 v[0:1], s[6:7], v32, s93, v[40:41]
	v_cndmask_b32_e32 v2, 0, v33, vcc
	v_cmp_lt_i32_e32 vcc, s9, v34
	ds_write_b32 v0, v2
	v_mad_u64_u32 v[0:1], s[6:7], v34, s93, v[40:41]
	v_cndmask_b32_e32 v2, 0, v35, vcc
	ds_write_b32 v0, v2
	v_mad_u64_u32 v[0:1], s[6:7], v36, s93, v[40:41]
	v_cmp_lt_i32_e32 vcc, s9, v36
	s_movk_i32 s6, 0x100
	s_nop 0
	v_cndmask_b32_e32 v2, 0, v37, vcc
	v_cmp_gt_i32_e32 vcc, s6, v8
	ds_write_b32 v0, v2
	s_and_saveexec_b64 s[6:7], vcc
	s_cbranch_execz .LBB0_301
	v_add_u32_e32 v0, s8, v8
	v_cmp_lt_i32_e32 vcc, -1, v0
	v_mov_b32_e32 v0, 0
	s_and_saveexec_b64 s[8:9], vcc
	s_cbranch_execz .LBB0_300
	s_ashr_i32 s13, s11, 31
	s_add_u32 s12, s11, s10
	v_ashrrev_i32_e32 v9, 31, v8
	s_addc_u32 s13, s13, 0
	v_lshl_add_u64 v[0:1], s[12:13], 0, v[8:9]
	v_lshl_add_u64 v[0:1], v[0:1], 2, v[12:13]
	global_load_dword v0, v[0:1], off offset:-512
